# EW1 and EW2 row loops: all x loads issued before the first wait, gain vectors preloaded once per phase, store-serialising vmcnt waits removed
# speedup vs baseline: 1.0066x; 1.0008x over previous
; __device__ __forceinline__ void ew_post(const bf16* Y, const float* xin, float* xout, const float* gpost, const float* gnext, bf16* H, int gw, int ngw, int lane) {
;     for (int m0 = EW_NR * gw; m0 < NTOK; m0 += EW_NR * ngw) {
;         f32x4 y[EW_NR][4], xv[EW_NR][4]; float s[EW_NR];
; #pragma unroll
;         for (int q = 0; q < EW_NR; ++q) { const v2u* yr = (const v2u*)(Y + (size_t)(m0 + q) * DM) + lane; const f32x4* xr = (const f32x4*)(xin + (size_t)(m0 + q) * DM) + lane;
; #pragma unroll
;             for (int j = 0; j < 4; ++j) { const v2u w = __builtin_nontemporal_load(yr + 64 * j); y[q][j] = (f32x4){bf_lo(w.x), bf_hi(w.x), bf_lo(w.y), bf_hi(w.y)}; xv[q][j] = __builtin_nontemporal_load(xr + 64 * j); } }
; __global__ void __launch_bounds__(NTHREADS, 2) fwd_megakernel(Args A) {
;     ...
;             else ew_post(Y, xres, xres, A.in[14] + (size_t)l * DM, l + 1 < DEPTH ? A.in[11] + (size_t)(l + 1) * DM : nullptr, H, gw, ngw, lane);
.LBB0_187:
	v_readlane_b32 s4, v255, 12
	v_readlane_b32 s5, v255, 13
	s_and_b64 vcc, exec, s[4:5]
	s_cbranch_vccz .LBB0_194
	s_cmpk_gt_i32 s96, 0x1fff
	s_mov_b32 s22, 0xfbfff000
	s_brev_b32 s23, 63
	s_cbranch_scc1 .LBB0_193
	v_and_b32_e32 v0, 64, v226
	v_add_u32_e32 v0, 64, v0
	v_xor_b32_e32 v1, 1, v226
	v_cmp_lt_i32_e32 vcc, v1, v0
	s_mov_b32 s7, s95
	v_readlane_b32 s56, v253, 30
	v_cndmask_b32_e32 v1, v226, v1, vcc
	v_lshlrev_b32_e32 v104, 2, v1
	v_xor_b32_e32 v1, 2, v226
	v_cmp_lt_i32_e32 vcc, v1, v0
	s_lshl_b64 s[4:5], s[6:7], 12
	v_readlane_b32 s62, v253, 36
	v_cndmask_b32_e32 v1, v226, v1, vcc
	v_lshlrev_b32_e32 v105, 2, v1
	v_xor_b32_e32 v1, 4, v226
	v_readlane_b32 s63, v253, 37
	s_add_u32 s6, s62, s4
	v_cmp_lt_i32_e32 vcc, v1, v0
	s_addc_u32 s7, s63, s5
	s_and_b64 s[4:5], s[10:11], exec
	v_cndmask_b32_e32 v1, v226, v1, vcc
	v_lshlrev_b32_e32 v106, 2, v1
	v_xor_b32_e32 v1, 8, v226
	s_cselect_b32 s5, s7, 0
	s_cselect_b32 s4, s6, 0
	s_ashr_i32 s89, s88, 31
	v_cmp_lt_i32_e32 vcc, v1, v0
	v_readlane_b32 s68, v253, 42
	s_lshl_b64 s[6:7], s[88:89], 12
	v_cndmask_b32_e32 v1, v226, v1, vcc
	v_readlane_b32 s69, v253, 43
	s_add_u32 s6, s68, s6
	v_lshlrev_b32_e32 v107, 2, v1
	v_xor_b32_e32 v1, 16, v226
	s_addc_u32 s7, s69, s7
	s_lshl_b32 s14, s96, 2
	v_cmp_lt_i32_e32 vcc, v1, v0
	s_cmp_lg_u64 s[4:5], 0
	v_lshlrev_b32_e32 v178, 4, v184
	v_cndmask_b32_e32 v1, v226, v1, vcc
	v_lshlrev_b32_e32 v108, 2, v1
	v_xor_b32_e32 v1, 32, v226
	s_cselect_b64 s[20:21], -1, 0
	s_ashr_i32 s15, s14, 31
	v_cmp_lt_i32_e32 vcc, v1, v0
	v_lshl_add_u64 v[64:65], s[6:7], 0, v[178:179]
	v_lshl_add_u64 v[66:67], s[4:5], 0, v[178:179]
	s_lshl_b64 s[4:5], s[14:15], 11
	v_readlane_b32 s6, v254, 11
	v_cndmask_b32_e32 v0, v226, v1, vcc
	s_add_u32 s4, s6, s4
	v_readlane_b32 s6, v254, 12
	v_lshlrev_b32_e32 v109, 2, v0
	v_lshlrev_b32_e32 v0, 3, v184
	v_mov_b32_e32 v1, v179
	s_addc_u32 s5, s6, s5
	v_lshl_add_u64 v[68:69], s[4:5], 0, v[0:1]
	s_lshl_b64 s[4:5], s[14:15], 12
	v_readlane_b32 s6, v254, 19
	v_readlane_b32 s60, v253, 34
	v_readlane_b32 s61, v253, 35
	v_readlane_b32 s70, v253, 44
	v_readlane_b32 s71, v253, 45
	s_add_u32 s4, s6, s4
	v_readlane_b32 s6, v254, 20
	v_readlane_b32 s66, v253, 40
	v_readlane_b32 s67, v253, 41
	v_readlane_b32 s60, v255, 2
	v_readlane_b32 s46, v255, 0
	v_readlane_b32 s42, v254, 62
	v_readlane_b32 s70, v254, 57
	v_readlane_b32 s68, v254, 55
	s_addc_u32 s5, s6, s5
	s_mov_b32 s24, 0x358637bd
	v_readlane_b32 s61, v255, 3
	v_readlane_b32 s47, v255, 1
	v_readlane_b32 s43, v254, 63
	v_readlane_b32 s16, v254, 13
	v_readlane_b32 s71, v254, 58
	v_readlane_b32 s66, v254, 53
	v_readlane_b32 s63, v254, 59
	v_readlane_b32 s89, v255, 8
	v_readlane_b32 s69, v254, 56
	v_lshl_add_u64 v[70:71], s[4:5], 0, v[178:179]
	v_readlane_b32 s57, v253, 31
	v_readlane_b32 s58, v253, 32
	v_readlane_b32 s59, v253, 33
	v_readlane_b32 s64, v253, 38
	v_readlane_b32 s65, v253, 39
	v_readlane_b32 s17, v254, 14
	v_readlane_b32 s67, v254, 54
	global_load_dwordx4 v[192:195], v[64:65], off
	global_load_dwordx4 v[196:199], v[64:65], off offset:1024
	global_load_dwordx4 v[200:203], v[64:65], off offset:2048
	global_load_dwordx4 v[204:207], v[64:65], off offset:3072
	s_and_b64 vcc, exec, s[20:21]
	s_cbranch_vccz .Lewb_nogn
	global_load_dwordx4 v[208:211], v[66:67], off
	global_load_dwordx4 v[212:215], v[66:67], off offset:1024
	global_load_dwordx4 v[216:219], v[66:67], off offset:2048
	global_load_dwordx4 v[220:223], v[66:67], off offset:3072
.Lewb_nogn:
	s_waitcnt vmcnt(0)
	s_branch .LBB0_191

; __device__ __forceinline__ void ew_post(const bf16* Y, const float* xin, float* xout, const float* gpost, const float* gnext, bf16* H, int gw, int ngw, int lane) {
;     for (int m0 = EW_NR * gw; m0 < NTOK; m0 += EW_NR * ngw) {
;         f32x4 y[EW_NR][4], xv[EW_NR][4]; float s[EW_NR];
; #pragma unroll
;         for (int q = 0; q < EW_NR; ++q) { const v2u* yr = (const v2u*)(Y + (size_t)(m0 + q) * DM) + lane; const f32x4* xr = (const f32x4*)(xin + (size_t)(m0 + q) * DM) + lane;
; #pragma unroll
;             for (int j = 0; j < 4; ++j) { const v2u w = __builtin_nontemporal_load(yr + 64 * j); y[q][j] = (f32x4){bf_lo(w.x), bf_hi(w.x), bf_lo(w.y), bf_hi(w.y)}; xv[q][j] = __builtin_nontemporal_load(xr + 64 * j); } }
; #pragma unroll
;         for (int q = 0; q < EW_NR; ++q) { s[q] = 0.f;
; #pragma unroll
;             for (int j = 0; j < 4; ++j) s[q] += (y[q][j].x * y[q][j].x + y[q][j].y * y[q][j].y) + (y[q][j].z * y[q][j].z + y[q][j].w * y[q][j].w); }
.LBB0_191:
	global_load_dwordx2 v[16:17], v[68:69], off offset:-4096 nt
	global_load_dwordx2 v[18:19], v[68:69], off offset:-2048 nt
	global_load_dwordx2 v[20:21], v[68:69], off nt
	v_add_co_u32_e32 v0, vcc, 0xfffff000, v68
	s_movk_i32 s4, 0xf000
	s_nop 0
	v_addc_co_u32_e32 v1, vcc, -1, v69, vcc
	global_load_dwordx2 v[22:23], v[0:1], off offset:-2048 nt
	global_load_dwordx2 v[24:25], v[0:1], off offset:-3584 nt
	global_load_dwordx2 v[26:27], v[0:1], off offset:-3072 nt
	global_load_dwordx2 v[28:29], v[0:1], off offset:-2560 nt
	global_load_dwordx2 v[30:31], v[0:1], off offset:-1536 nt
	global_load_dwordx2 v[42:43], v[68:69], off offset:-3584 nt
	global_load_dwordx2 v[84:85], v[68:69], off offset:-3072 nt
	global_load_dwordx2 v[94:95], v[68:69], off offset:-2560 nt
	global_load_dwordx4 v[4:7], v[70:71], off offset:-3072 nt
	global_load_dwordx2 v[38:39], v[0:1], off offset:-1024 nt
	global_load_dwordx2 v[46:47], v[68:69], off offset:-1536 nt
	global_load_dwordx2 v[86:87], v[68:69], off offset:-1024 nt
	global_load_dwordx2 v[88:89], v[68:69], off offset:-512 nt
	global_load_dwordx2 v[40:41], v[0:1], off offset:-512 nt
	v_add_co_u32_e32 v36, vcc, s4, v70
	s_movk_i32 s6, 0xe000
	s_nop 0
	v_addc_co_u32_e32 v37, vcc, -1, v71, vcc
	v_add_co_u32_e32 v48, vcc, 0xffffd000, v70
	s_mov_b64 s[4:5], vcc
	v_addc_co_u32_e64 v49, s[4:5], -1, v71, s[4:5]
	global_load_dwordx4 v[0:3], v[48:49], off offset:-3072 nt
	v_add_co_u32_e32 v50, vcc, s6, v70
	global_load_dwordx4 v[8:11], v[36:37], off offset:-3072 nt
	s_nop 0
	v_addc_co_u32_e32 v51, vcc, -1, v71, vcc
	global_load_dwordx4 v[12:15], v[50:51], off offset:-3072 nt
	global_load_dwordx4 v[124:127], v[48:49], off offset:-2048 nt
	global_load_dwordx4 v[128:131], v[50:51], off offset:-2048 nt
	global_load_dwordx4 v[132:135], v[36:37], off offset:-2048 nt
	global_load_dwordx4 v[136:139], v[70:71], off offset:-2048 nt
	global_load_dwordx4 v[140:143], v[48:49], off offset:-1024 nt
	global_load_dwordx4 v[144:147], v[50:51], off offset:-1024 nt
	global_load_dwordx4 v[148:151], v[36:37], off offset:-1024 nt
	global_load_dwordx4 v[152:155], v[70:71], off offset:-1024 nt
	global_load_dwordx4 v[156:159], v[48:49], off nt
	global_load_dwordx4 v[160:163], v[70:71], off offset:-4096 nt
	global_load_dwordx4 v[164:167], v[50:51], off nt
	global_load_dwordx4 v[168:171], v[70:71], off nt
	s_waitcnt vmcnt(0)
	v_lshlrev_b32_e32 v79, 16, v22
	v_and_b32_e32 v59, 0xffff0000, v22
	v_lshlrev_b32_e32 v60, 16, v23
	v_and_b32_e32 v61, 0xffff0000, v23
	v_lshlrev_b32_e32 v54, 16, v17
	v_and_b32_e32 v55, 0xffff0000, v17
	v_lshlrev_b32_e32 v72, 16, v19
	v_and_b32_e32 v73, 0xffff0000, v19
	v_and_b32_e32 v17, 0xffff0000, v24
	v_and_b32_e32 v19, 0xffff0000, v25
	v_lshlrev_b32_e32 v83, 16, v16
	v_and_b32_e32 v53, 0xffff0000, v16
	v_lshlrev_b32_e32 v81, 16, v18
	v_and_b32_e32 v63, 0xffff0000, v18
	v_lshlrev_b32_e32 v16, 16, v24
	v_lshlrev_b32_e32 v18, 16, v25
	v_and_b32_e32 v23, 0xffff0000, v27
	v_and_b32_e32 v22, 0xffff0000, v26
	v_lshlrev_b32_e32 v32, 16, v28
	v_and_b32_e32 v33, 0xffff0000, v28
	v_mul_f32_e32 v24, v19, v19
	v_mul_f32_e32 v28, v17, v17
	v_mov_b32_e32 v25, v79
	v_lshlrev_b32_e32 v77, 16, v20
	v_and_b32_e32 v57, 0xffff0000, v20
	v_lshlrev_b32_e32 v74, 16, v21
	v_and_b32_e32 v75, 0xffff0000, v21
	v_lshlrev_b32_e32 v21, 16, v27
	v_lshlrev_b32_e32 v20, 16, v26
	v_lshlrev_b32_e32 v34, 16, v29
	v_and_b32_e32 v35, 0xffff0000, v29
	v_pk_mul_f32 v[26:27], v[22:23], v[22:23]
	v_pk_fma_f32 v[90:91], v[18:19], v[18:19], v[24:25] op_sel_hi:[1,1,0]
	v_pk_fma_f32 v[28:29], v[16:17], v[16:17], v[28:29] op_sel_hi:[1,1,0]
	v_mul_f32_e32 v44, v33, v33
	v_mul_f32_e32 v52, v35, v35
	v_pk_fma_f32 v[26:27], v[20:21], v[20:21], v[26:27]
	v_mov_b32_e32 v78, v28
	v_mov_b32_e32 v24, v90
	v_mul_f32_e32 v56, v59, v59
	v_mul_f32_e32 v58, v60, v60
	v_mul_f32_e32 v62, v61, v61
	v_pk_fma_f32 v[44:45], v[32:33], v[32:33], v[44:45] op_sel_hi:[1,1,0]
	v_pk_fma_f32 v[92:93], v[34:35], v[34:35], v[52:53] op_sel_hi:[1,1,0]
	v_pk_add_f32 v[28:29], v[28:29], v[90:91]
	v_pk_add_f32 v[26:27], v[26:27], v[26:27] op_sel:[0,1] op_sel_hi:[1,0]
	v_pk_mul_f32 v[24:25], v[78:79], v[24:25]
	v_mov_b32_e32 v45, v58
	v_mov_b32_e32 v27, v56
	v_mov_b32_e32 v29, v25
	v_mov_b32_e32 v93, v62
	v_pk_add_f32 v[24:25], v[28:29], v[26:27]
	v_pk_add_f32 v[26:27], v[44:45], v[92:93]
	v_and_b32_e32 v45, 0xffff0000, v30
	v_and_b32_e32 v93, 0xffff0000, v31
	v_pk_add_f32 v[102:103], v[24:25], v[26:27]
	v_lshlrev_b32_e32 v44, 16, v30
	v_lshlrev_b32_e32 v92, 16, v31
	v_mul_f32_e32 v24, v93, v93
	v_and_b32_e32 v27, 0xffff0000, v39
	v_and_b32_e32 v26, 0xffff0000, v38
	v_mul_f32_e32 v52, v45, v45
	v_pk_fma_f32 v[28:29], v[92:93], v[92:93], v[24:25] op_sel_hi:[1,1,0]
	v_lshlrev_b32_e32 v25, 16, v39
	v_lshlrev_b32_e32 v24, 16, v38
	v_pk_mul_f32 v[30:31], v[26:27], v[26:27]
	v_pk_fma_f32 v[90:91], v[44:45], v[44:45], v[52:53] op_sel_hi:[1,1,0]
	v_pk_fma_f32 v[30:31], v[24:25], v[24:25], v[30:31]
	v_mov_b32_e32 v82, v90
	v_mov_b32_e32 v96, v28
	v_mov_b32_e32 v97, v83
	v_mul_f32_e32 v56, v53, v53
	v_pk_add_f32 v[28:29], v[90:91], v[28:29]
	v_pk_mul_f32 v[90:91], v[82:83], v[96:97]
	v_pk_add_f32 v[30:31], v[30:31], v[30:31] op_sel:[0,1] op_sel_hi:[1,0]
	v_lshlrev_b32_e32 v38, 16, v40
	v_and_b32_e32 v39, 0xffff0000, v40
	v_lshlrev_b32_e32 v40, 16, v41
	v_and_b32_e32 v41, 0xffff0000, v41
	v_mov_b32_e32 v29, v91
	v_mov_b32_e32 v31, v56
	v_pk_add_f32 v[28:29], v[28:29], v[30:31]
	v_mul_f32_e32 v30, v39, v39
	v_mul_f32_e32 v52, v41, v41
	v_mul_f32_e32 v58, v54, v54
	v_mul_f32_e32 v62, v55, v55
	v_pk_fma_f32 v[30:31], v[38:39], v[38:39], v[30:31] op_sel_hi:[1,1,0]
	v_pk_fma_f32 v[90:91], v[40:41], v[40:41], v[52:53] op_sel_hi:[1,1,0]
; __device__ __forceinline__ void ew_post(const bf16* Y, const float* xin, float* xout, const float* gpost, const float* gnext, bf16* H, int gw, int ngw, int lane) {
;     ...
;         for (int q = 0; q < EW_NR; ++q) { s[q] = 0.f;
; #pragma unroll
;             for (int j = 0; j < 4; ++j) s[q] += (y[q][j].x * y[q][j].x + y[q][j].y * y[q][j].y) + (y[q][j].z * y[q][j].z + y[q][j].w * y[q][j].w); }
;         float rstd[EW_NR], s2[EW_NR];
; #pragma unroll
;         for (int q = 0; q < EW_NR; ++q) { rstd[q] = rsqrtf(wave_sum(s[q]) * (1.f / DM) + RMS_EPS); s2[q] = 0.f; }
; #pragma unroll
;         for (int j = 0; j < 4; ++j) { const f32x4 g = *((const f32x4*)gpost + lane + 64 * j);
	v_mov_b32_e32 v31, v58
	v_mov_b32_e32 v91, v62
	v_pk_add_f32 v[30:31], v[30:31], v[90:91]
	v_and_b32_e32 v97, 0xffff0000, v43
	v_pk_add_f32 v[114:115], v[28:29], v[30:31]
	v_and_b32_e32 v91, 0xffff0000, v42
	v_lshlrev_b32_e32 v96, 16, v43
	v_mul_f32_e32 v28, v97, v97
	v_and_b32_e32 v31, 0xffff0000, v85
	v_and_b32_e32 v30, 0xffff0000, v84
	v_lshlrev_b32_e32 v90, 16, v42
	v_pk_fma_f32 v[98:99], v[96:97], v[96:97], v[28:29] op_sel_hi:[1,1,0]
	v_lshlrev_b32_e32 v29, 16, v85
	v_lshlrev_b32_e32 v28, 16, v84
	v_pk_mul_f32 v[42:43], v[30:31], v[30:31]
	v_mul_f32_e32 v52, v91, v91
	v_pk_fma_f32 v[100:101], v[28:29], v[28:29], v[42:43]
	v_lshlrev_b32_e32 v42, 16, v94
	v_and_b32_e32 v43, 0xffff0000, v94
	v_lshlrev_b32_e32 v84, 16, v95
	v_and_b32_e32 v85, 0xffff0000, v95
	v_pk_fma_f32 v[94:95], v[90:91], v[90:91], v[52:53] op_sel_hi:[1,1,0]
	v_mov_b32_e32 v110, v98
	v_mov_b32_e32 v80, v94
	v_mov_b32_e32 v111, v81
	v_pk_add_f32 v[94:95], v[94:95], v[98:99]
	v_pk_mul_f32 v[98:99], v[80:81], v[110:111]
	s_nop 1
	v_mov_b32_e32 v110, v192
	v_mov_b32_e32 v111, v193
	v_mov_b32_e32 v112, v194
	v_mov_b32_e32 v113, v195
	v_mul_f32_e32 v56, v63, v63
	v_mov_b32_e32 v95, v99
	v_pk_add_f32 v[98:99], v[100:101], v[100:101] op_sel:[0,1] op_sel_hi:[1,0]
	v_mul_f32_e32 v52, v43, v43
	v_mov_b32_e32 v99, v56
	v_pk_add_f32 v[94:95], v[94:95], v[98:99]
	v_pk_fma_f32 v[98:99], v[42:43], v[42:43], v[52:53] op_sel_hi:[1,1,0]
	v_mul_f32_e32 v52, v85, v85
	v_mul_f32_e32 v58, v72, v72
	v_mul_f32_e32 v62, v73, v73
	v_pk_fma_f32 v[100:101], v[84:85], v[84:85], v[52:53] op_sel_hi:[1,1,0]
	v_mov_b32_e32 v99, v58
	v_mov_b32_e32 v101, v62
	v_pk_add_f32 v[98:99], v[98:99], v[100:101]
	v_and_b32_e32 v101, 0xffff0000, v47
	v_pk_add_f32 v[116:117], v[94:95], v[98:99]
	v_and_b32_e32 v99, 0xffff0000, v46
	v_lshlrev_b32_e32 v98, 16, v46
	v_lshlrev_b32_e32 v100, 16, v47
	v_mul_f32_e32 v46, v101, v101
	v_mul_f32_e32 v52, v99, v99
	v_pk_fma_f32 v[118:119], v[100:101], v[100:101], v[46:47] op_sel_hi:[1,1,0]
	v_pk_fma_f32 v[122:123], v[98:99], v[98:99], v[52:53] op_sel_hi:[1,1,0]
	v_and_b32_e32 v95, 0xffff0000, v87
	v_mov_b32_e32 v76, v122
	v_pk_add_f32 v[122:123], v[122:123], v[118:119]
	v_mov_b32_e32 v119, v77
	v_pk_mul_f32 v[118:119], v[76:77], v[118:119]
	v_and_b32_e32 v94, 0xffff0000, v86
	v_mov_b32_e32 v123, v119
	v_mov_b32_e32 v118, v114
	v_mov_b32_e32 v119, v102
	v_mov_b32_e32 v102, v115
	v_pk_add_f32 v[102:103], v[118:119], v[102:103]
	ds_bpermute_b32 v115, v104, v103
	ds_bpermute_b32 v114, v104, v102
	v_lshlrev_b32_e32 v47, 16, v87
	v_lshlrev_b32_e32 v46, 16, v86
	v_pk_mul_f32 v[86:87], v[94:95], v[94:95]
	v_mul_f32_e32 v56, v57, v57
	v_pk_fma_f32 v[120:121], v[46:47], v[46:47], v[86:87]
	v_and_b32_e32 v87, 0xffff0000, v88
	s_waitcnt lgkmcnt(0)
	v_pk_add_f32 v[102:103], v[102:103], v[114:115]
	v_lshlrev_b32_e32 v86, 16, v88
	v_lshlrev_b32_e32 v88, 16, v89
	v_and_b32_e32 v89, 0xffff0000, v89
	v_pk_add_f32 v[118:119], v[120:121], v[120:121] op_sel:[0,1] op_sel_hi:[1,0]
	ds_bpermute_b32 v115, v105, v103
	ds_bpermute_b32 v114, v105, v102
	v_mul_f32_e32 v52, v87, v87
	v_mov_b32_e32 v119, v56
	v_pk_fma_f32 v[120:121], v[86:87], v[86:87], v[52:53] op_sel_hi:[1,1,0]
	v_mul_f32_e32 v52, v89, v89
	v_mul_f32_e32 v58, v74, v74
	v_mul_f32_e32 v62, v75, v75
	v_pk_add_f32 v[118:119], v[122:123], v[118:119]
	v_pk_fma_f32 v[122:123], v[88:89], v[88:89], v[52:53] op_sel_hi:[1,1,0]
	v_mov_b32_e32 v121, v58
	v_mov_b32_e32 v123, v62
	v_pk_add_f32 v[120:121], v[120:121], v[122:123]
	s_waitcnt lgkmcnt(0)
	v_pk_add_f32 v[102:103], v[102:103], v[114:115]
	v_pk_add_f32 v[118:119], v[118:119], v[120:121]
	ds_bpermute_b32 v115, v106, v103
	ds_bpermute_b32 v114, v106, v102
	v_mov_b32_e32 v120, v118
	v_mov_b32_e32 v121, v116
	v_mov_b32_e32 v116, v119
	v_pk_add_f32 v[116:117], v[120:121], v[116:117]
	ds_bpermute_b32 v119, v104, v117
	ds_bpermute_b32 v118, v104, v116
	s_waitcnt lgkmcnt(2)
	v_pk_add_f32 v[102:103], v[102:103], v[114:115]
	ds_bpermute_b32 v115, v107, v103
	ds_bpermute_b32 v114, v107, v102
	v_mov_b32_e32 v62, v81
	s_waitcnt lgkmcnt(2)
	v_pk_add_f32 v[118:119], v[116:117], v[118:119]
	ds_bpermute_b32 v121, v105, v119
	ds_bpermute_b32 v120, v105, v118
	s_waitcnt lgkmcnt(2)
	v_pk_add_f32 v[102:103], v[102:103], v[114:115]
	ds_bpermute_b32 v115, v108, v103
	ds_bpermute_b32 v114, v108, v102
	s_waitcnt lgkmcnt(2)
	v_pk_add_f32 v[118:119], v[118:119], v[120:121]
	ds_bpermute_b32 v121, v106, v119
	ds_bpermute_b32 v120, v106, v118
	s_waitcnt lgkmcnt(2)
	v_pk_add_f32 v[102:103], v[102:103], v[114:115]
	ds_bpermute_b32 v123, v109, v103
	ds_bpermute_b32 v122, v109, v102
	s_nop 1
	v_mov_b32_e32 v114, v124
	v_mov_b32_e32 v115, v125
	v_mov_b32_e32 v116, v126
	v_mov_b32_e32 v117, v127
	s_waitcnt lgkmcnt(2)
	v_pk_add_f32 v[118:119], v[118:119], v[120:121]
	ds_bpermute_b32 v121, v107, v119
	ds_bpermute_b32 v120, v107, v118
	s_waitcnt lgkmcnt(2)
	v_pk_add_f32 v[102:103], v[102:103], v[122:123]
	v_mov_b64_e32 v[122:123], s[24:25]
	v_pk_fma_f32 v[102:103], v[102:103], s[44:45], v[122:123] op_sel_hi:[1,0,0]
	s_waitcnt lgkmcnt(0)
	v_pk_add_f32 v[118:119], v[118:119], v[120:121]
	v_mul_f32_e32 v52, 0x4b800000, v103
	v_cmp_gt_f32_e32 vcc, s3, v103
	ds_bpermute_b32 v121, v108, v119
	ds_bpermute_b32 v120, v108, v118
	v_cndmask_b32_e32 v52, v103, v52, vcc
	v_rsq_f32_e32 v52, v52
	v_mul_f32_e32 v56, 0x4b800000, v102
	v_cmp_gt_f32_e64 s[4:5], s3, v102
	v_mul_f32_e32 v58, 0x45800000, v52
	s_nop 0
	v_cndmask_b32_e64 v56, v102, v56, s[4:5]
	s_waitcnt lgkmcnt(0)
; __device__ __forceinline__ void ew_post(const bf16* Y, const float* xin, float* xout, const float* gpost, const float* gnext, bf16* H, int gw, int ngw, int lane) {
;     ...
; #pragma unroll
;         for (int j = 0; j < 4; ++j) { const f32x4 g = *((const f32x4*)gpost + lane + 64 * j);
; #pragma unroll
;             for (int q = 0; q < EW_NR; ++q) { xv[q][j] = xv[q][j] + y[q][j] * rstd[q] * g; __builtin_nontemporal_store(xv[q][j], (f32x4*)(xout + (size_t)(m0 + q) * DM) + lane + 64 * j);
;                 s2[q] += (xv[q][j].x * xv[q][j].x + xv[q][j].y * xv[q][j].y) + (xv[q][j].z * xv[q][j].z + xv[q][j].w * xv[q][j].w); } }
	v_pk_add_f32 v[102:103], v[118:119], v[120:121]
	v_cndmask_b32_e32 v76, v52, v58, vcc
	v_rsq_f32_e32 v52, v56
	ds_bpermute_b32 v119, v109, v103
	ds_bpermute_b32 v118, v109, v102
	v_pk_mul_f32 v[16:17], v[76:77], v[16:17] op_sel_hi:[0,1]
	v_pk_fma_f32 v[0:1], v[16:17], v[110:111], v[0:1]
	v_mul_f32_e32 v16, 0x45800000, v52
	v_cndmask_b32_e64 v78, v52, v16, s[4:5]
	s_waitcnt lgkmcnt(0)
	v_pk_add_f32 v[16:17], v[102:103], v[118:119]
	v_pk_mul_f32 v[18:19], v[76:77], v[18:19] op_sel_hi:[0,1]
	v_pk_fma_f32 v[16:17], v[16:17], s[44:45], v[122:123] op_sel_hi:[1,0,0]
	v_pk_fma_f32 v[2:3], v[18:19], v[112:113], v[2:3]
	v_mul_f32_e32 v18, 0x4b800000, v17
	v_cmp_gt_f32_e32 vcc, s3, v17
	s_nop 1
	v_mov_b32_e32 v118, v128
	v_mov_b32_e32 v119, v129
	v_mov_b32_e32 v120, v130
	v_mov_b32_e32 v121, v131
	v_pk_mul_f32 v[34:35], v[76:77], v[34:35] op_sel_hi:[0,1]
	v_cndmask_b32_e32 v17, v17, v18, vcc
	v_rsq_f32_e32 v17, v17
	v_pk_mul_f32 v[18:19], v[78:79], v[44:45] op_sel_hi:[0,1]
	v_pk_fma_f32 v[12:13], v[18:19], v[110:111], v[12:13]
	v_pk_mul_f32 v[44:45], v[78:79], v[92:93] op_sel_hi:[0,1]
	v_mul_f32_e32 v18, 0x45800000, v17
	v_cndmask_b32_e32 v80, v17, v18, vcc
	v_mul_f32_e32 v17, 0x4b800000, v16
	v_cmp_gt_f32_e32 vcc, s3, v16
	v_pk_fma_f32 v[14:15], v[44:45], v[112:113], v[14:15]
	v_pk_mul_f32 v[18:19], v[80:81], v[96:97] op_sel_hi:[0,1]
	v_cndmask_b32_e32 v16, v16, v17, vcc
	v_rsq_f32_e32 v44, v16
	v_pk_mul_f32 v[16:17], v[80:81], v[90:91] op_sel_hi:[0,1]
	s_nop 1
	v_mov_b32_e32 v90, v132
	v_mov_b32_e32 v91, v133
	v_mov_b32_e32 v92, v134
	v_mov_b32_e32 v93, v135
	v_pk_fma_f32 v[16:17], v[110:111], v[16:17], v[8:9]
	v_mul_f32_e32 v8, 0x45800000, v44
	v_cndmask_b32_e32 v82, v44, v8, vcc
	v_pk_fma_f32 v[18:19], v[112:113], v[18:19], v[10:11]
	v_pk_mul_f32 v[8:9], v[82:83], v[98:99] op_sel_hi:[0,1]
	v_pk_mul_f32 v[10:11], v[82:83], v[100:101] op_sel_hi:[0,1]
	global_store_dwordx4 v[48:49], v[0:3], off offset:-3072 nt
	global_store_dwordx4 v[50:51], v[12:15], off offset:-3072 nt
	global_store_dwordx4 v[36:37], v[16:19], off offset:-3072 nt
	v_pk_fma_f32 v[6:7], v[112:113], v[10:11], v[6:7]
	v_pk_fma_f32 v[4:5], v[110:111], v[8:9], v[4:5]
	s_nop 1
	v_mov_b32_e32 v96, v136
	v_mov_b32_e32 v97, v137
	v_mov_b32_e32 v98, v138
	v_mov_b32_e32 v99, v139
	v_mov_b32_e32 v8, v21
	global_store_dwordx4 v[70:71], v[4:7], off offset:-3072 nt
	s_nop 1
	v_mov_b32_e32 v100, v196
	v_mov_b32_e32 v101, v197
	v_mov_b32_e32 v102, v198
	v_mov_b32_e32 v103, v199
	s_nop 1
	v_mov_b32_e32 v110, v140
	v_mov_b32_e32 v111, v141
	v_mov_b32_e32 v112, v142
	v_mov_b32_e32 v113, v143
	v_mov_b32_e32 v9, v23
	v_mov_b32_e32 v21, v22
	v_pk_mul_f32 v[10:11], v[76:77], v[8:9] op_sel_hi:[0,1]
	v_pk_mul_f32 v[8:9], v[76:77], v[20:21] op_sel_hi:[0,1]
	v_mov_b32_e32 v20, v25
	v_mov_b32_e32 v21, v27
	v_mov_b32_e32 v25, v26
	v_pk_mul_f32 v[22:23], v[78:79], v[20:21] op_sel_hi:[0,1]
	v_pk_mul_f32 v[20:21], v[78:79], v[24:25] op_sel_hi:[0,1]
	v_mov_b32_e32 v24, v29
	v_mov_b32_e32 v25, v31
	v_mov_b32_e32 v29, v30
	v_pk_mul_f32 v[26:27], v[80:81], v[24:25] op_sel_hi:[0,1]
	v_pk_mul_f32 v[24:25], v[80:81], v[28:29] op_sel_hi:[0,1]
	v_mov_b32_e32 v28, v47
	v_mov_b32_e32 v29, v95
	v_mov_b32_e32 v47, v94
	v_pk_mul_f32 v[30:31], v[82:83], v[28:29] op_sel_hi:[0,1]
	v_pk_mul_f32 v[28:29], v[82:83], v[46:47] op_sel_hi:[0,1]
	v_pk_mul_f32 v[32:33], v[76:77], v[32:33] op_sel_hi:[0,1]
	v_pk_mul_f32 v[40:41], v[78:79], v[40:41] op_sel_hi:[0,1]
	v_pk_mul_f32 v[38:39], v[78:79], v[38:39] op_sel_hi:[0,1]
	v_mov_b32_e32 v56, v77
	v_mov_b32_e32 v58, v79
	v_mov_b32_e32 v52, v83
	v_pk_mul_f32 v[74:75], v[82:83], v[74:75] op_sel_hi:[0,1]
	v_pk_mul_f32 v[58:59], v[76:77], v[58:59] op_sel_hi:[0,1]
	v_pk_mul_f32 v[72:73], v[80:81], v[72:73] op_sel_hi:[0,1]
	v_pk_mul_f32 v[54:55], v[78:79], v[54:55] op_sel_hi:[0,1]
	v_pk_mul_f32 v[52:53], v[78:79], v[52:53] op_sel_hi:[0,1]
	s_andn2_b64 vcc, exec, s[20:21]
	v_pk_fma_f32 v[8:9], v[8:9], v[100:101], v[114:115]
	v_pk_fma_f32 v[10:11], v[10:11], v[102:103], v[116:117]
	v_pk_fma_f32 v[20:21], v[20:21], v[100:101], v[118:119]
	v_pk_fma_f32 v[22:23], v[22:23], v[102:103], v[120:121]
	v_pk_fma_f32 v[24:25], v[100:101], v[24:25], v[90:91]
	v_pk_fma_f32 v[26:27], v[102:103], v[26:27], v[92:93]
	v_pk_fma_f32 v[28:29], v[100:101], v[28:29], v[96:97]
	v_pk_fma_f32 v[30:31], v[102:103], v[30:31], v[98:99]
	global_store_dwordx4 v[48:49], v[8:11], off offset:-2048 nt
	global_store_dwordx4 v[50:51], v[20:23], off offset:-2048 nt
	global_store_dwordx4 v[36:37], v[24:27], off offset:-2048 nt
	global_store_dwordx4 v[70:71], v[28:31], off offset:-2048 nt
	s_nop 1
	v_mov_b32_e32 v90, v200
	v_mov_b32_e32 v91, v201
	v_mov_b32_e32 v92, v202
	v_mov_b32_e32 v93, v203
	s_nop 1
	v_mov_b32_e32 v44, v144
	v_mov_b32_e32 v45, v145
	v_mov_b32_e32 v46, v146
	v_mov_b32_e32 v47, v147
	s_nop 1
	v_mov_b32_e32 v94, v148
	v_mov_b32_e32 v95, v149
	v_mov_b32_e32 v96, v150
	v_mov_b32_e32 v97, v151
	s_nop 1
	v_mov_b32_e32 v98, v152
	v_mov_b32_e32 v99, v153
	v_mov_b32_e32 v100, v154
	v_mov_b32_e32 v101, v155
	s_nop 1
	v_mov_b32_e32 v114, v156
	v_mov_b32_e32 v115, v157
	v_mov_b32_e32 v116, v158
	v_mov_b32_e32 v117, v159
	s_nop 1
	v_mov_b32_e32 v118, v160
	v_mov_b32_e32 v119, v161
	v_mov_b32_e32 v120, v162
	v_mov_b32_e32 v121, v163
	v_pk_fma_f32 v[32:33], v[32:33], v[90:91], v[110:111]
	v_pk_fma_f32 v[34:35], v[34:35], v[92:93], v[112:113]
	v_pk_fma_f32 v[44:45], v[38:39], v[90:91], v[44:45]
	v_pk_fma_f32 v[46:47], v[40:41], v[92:93], v[46:47]
	v_pk_mul_f32 v[38:39], v[80:81], v[84:85] op_sel_hi:[0,1]
	v_pk_mul_f32 v[40:41], v[80:81], v[42:43] op_sel_hi:[0,1]
	s_nop 1
	v_mov_b32_e32 v110, v164
	v_mov_b32_e32 v111, v165
; __device__ __forceinline__ void ew_post(const bf16* Y, const float* xin, float* xout, const float* gpost, const float* gnext, bf16* H, int gw, int ngw, int lane) {
;     ...
;             for (int q = 0; q < EW_NR; ++q) { xv[q][j] = xv[q][j] + y[q][j] * rstd[q] * g; __builtin_nontemporal_store(xv[q][j], (f32x4*)(xout + (size_t)(m0 + q) * DM) + lane + 64 * j);
;                 s2[q] += (xv[q][j].x * xv[q][j].x + xv[q][j].y * xv[q][j].y) + (xv[q][j].z * xv[q][j].z + xv[q][j].w * xv[q][j].w); } }
;         if (gnext) {
;             float r2[EW_NR];
; #pragma unroll
;             for (int q = 0; q < EW_NR; ++q) r2[q] = rsqrtf(wave_sum(s2[q]) * (1.f / DM) + RMS_EPS);
; #pragma unroll
;             for (int j = 0; j < 4; ++j) { const f32x4 g = *((const f32x4*)gnext + lane + 64 * j);
	v_mov_b32_e32 v112, v166
	v_mov_b32_e32 v113, v167
	v_pk_fma_f32 v[40:41], v[40:41], v[90:91], v[94:95]
	v_pk_fma_f32 v[42:43], v[38:39], v[92:93], v[96:97]
	global_store_dwordx4 v[48:49], v[32:35], off offset:-1024 nt
	global_store_dwordx4 v[50:51], v[44:47], off offset:-1024 nt
	global_store_dwordx4 v[36:37], v[40:43], off offset:-1024 nt
	v_pk_mul_f32 v[38:39], v[82:83], v[88:89] op_sel_hi:[0,1]
	v_pk_mul_f32 v[36:37], v[82:83], v[86:87] op_sel_hi:[0,1]
	v_pk_fma_f32 v[36:37], v[90:91], v[36:37], v[98:99]
	v_pk_fma_f32 v[38:39], v[92:93], v[38:39], v[100:101]
	global_store_dwordx4 v[70:71], v[36:39], off offset:-1024 nt
	s_nop 1
	v_mov_b32_e32 v88, v204
	v_mov_b32_e32 v89, v205
	v_mov_b32_e32 v90, v206
	v_mov_b32_e32 v91, v207
	s_nop 1
	v_mov_b32_e32 v84, v168
	v_mov_b32_e32 v85, v169
	v_mov_b32_e32 v86, v170
	v_mov_b32_e32 v87, v171
	v_pk_mul_f32 v[82:83], v[82:83], v[56:57] op_sel_hi:[0,1]
	v_pk_mul_f32 v[56:57], v[76:77], v[60:61] op_sel_hi:[0,1]
	v_pk_mul_f32 v[80:81], v[80:81], v[62:63] op_sel_hi:[0,1]
	v_pk_fma_f32 v[60:61], v[58:59], v[88:89], v[114:115]
	v_pk_fma_f32 v[62:63], v[56:57], v[90:91], v[116:117]
	v_pk_fma_f32 v[56:57], v[52:53], v[88:89], v[110:111]
	v_pk_fma_f32 v[58:59], v[54:55], v[90:91], v[112:113]
	v_pk_fma_f32 v[52:53], v[80:81], v[88:89], v[118:119]
	v_pk_fma_f32 v[54:55], v[72:73], v[90:91], v[120:121]
	global_store_dwordx4 v[48:49], v[60:63], off nt
	global_store_dwordx4 v[50:51], v[56:59], off nt
	global_store_dwordx4 v[70:71], v[52:55], off offset:-4096 nt
	v_pk_fma_f32 v[48:49], v[82:83], v[88:89], v[84:85]
	v_pk_fma_f32 v[50:51], v[74:75], v[90:91], v[86:87]
	global_store_dwordx4 v[70:71], v[48:51], off nt
	s_cbranch_vccnz .LBB0_190
	v_pk_mul_f32 v[72:73], v[6:7], v[6:7]
	v_pk_mul_f32 v[74:75], v[4:5], v[4:5]
	v_mul_f32_e32 v80, v49, v49
	v_pk_mov_b32 v[76:77], v[74:75], v[72:73] op_sel:[1,0]
	v_mov_b32_e32 v75, v73
	v_pk_add_f32 v[72:73], v[76:77], v[74:75]
	v_pk_mul_f32 v[74:75], v[30:31], v[30:31]
	v_pk_mul_f32 v[76:77], v[28:29], v[28:29]
	v_mul_f32_e32 v81, v50, v50
	v_pk_mov_b32 v[78:79], v[76:77], v[74:75] op_sel:[1,0]
	v_mov_b32_e32 v77, v75
	v_pk_add_f32 v[74:75], v[78:79], v[76:77]
	v_mul_f32_e32 v76, v37, v37
	v_mul_f32_e32 v78, v48, v48
	v_pk_fma_f32 v[76:77], v[36:37], v[36:37], v[76:77] op_sel_hi:[1,1,0]
	v_mul_f32_e32 v82, v51, v51
	v_mov_b32_e32 v77, v78
	v_mul_f32_e32 v78, v39, v39
	v_pk_fma_f32 v[78:79], v[38:39], v[38:39], v[78:79] op_sel_hi:[1,1,0]
	v_pk_add_f32 v[72:73], v[72:73], v[72:73] op_sel:[0,1] op_sel_hi:[1,0]
	v_pk_add_f32 v[74:75], v[74:75], v[74:75] op_sel:[0,1] op_sel_hi:[1,0]
	v_mov_b32_e32 v79, v80
	v_mov_b32_e32 v73, v81
	v_mov_b32_e32 v75, v82
	v_pk_add_f32 v[76:77], v[76:77], v[78:79]
	v_pk_add_f32 v[72:73], v[72:73], v[74:75]
	v_pk_mul_f32 v[74:75], v[16:17], v[16:17]
	v_pk_add_f32 v[76:77], v[76:77], v[72:73]
	v_pk_mul_f32 v[72:73], v[18:19], v[18:19]
	v_mul_f32_e32 v88, v53, v53
	v_pk_mov_b32 v[78:79], v[74:75], v[72:73] op_sel:[1,0]
	v_mov_b32_e32 v75, v73
	v_pk_add_f32 v[72:73], v[78:79], v[74:75]
	v_pk_mul_f32 v[74:75], v[26:27], v[26:27]
	v_pk_mul_f32 v[78:79], v[24:25], v[24:25]
	v_mul_f32_e32 v89, v54, v54
	v_pk_mov_b32 v[80:81], v[78:79], v[74:75] op_sel:[1,0]
	v_mov_b32_e32 v79, v75
	v_pk_add_f32 v[74:75], v[80:81], v[78:79]
	v_mul_f32_e32 v80, v52, v52
	v_pk_add_f32 v[78:79], v[72:73], v[72:73] op_sel:[0,1] op_sel_hi:[1,0]
	v_pk_mul_f32 v[72:73], v[14:15], v[14:15]
	v_mov_b32_e32 v79, v80
	v_pk_mul_f32 v[80:81], v[12:13], v[12:13]
	v_mul_f32_e32 v90, v55, v55
	v_pk_mov_b32 v[82:83], v[80:81], v[72:73] op_sel:[1,0]
	v_mov_b32_e32 v81, v73
	v_pk_add_f32 v[72:73], v[82:83], v[80:81]
	v_pk_mul_f32 v[80:81], v[22:23], v[22:23]
	v_pk_mul_f32 v[82:83], v[20:21], v[20:21]
	v_pk_add_f32 v[72:73], v[72:73], v[72:73] op_sel:[0,1] op_sel_hi:[1,0]
	v_pk_mov_b32 v[84:85], v[82:83], v[80:81] op_sel:[1,0]
	v_mov_b32_e32 v83, v81
	v_pk_add_f32 v[80:81], v[84:85], v[82:83]
	v_mul_f32_e32 v82, v56, v56
	v_mul_f32_e32 v83, v57, v57
	v_pk_add_f32 v[80:81], v[80:81], v[80:81] op_sel:[0,1] op_sel_hi:[1,0]
	v_mov_b32_e32 v73, v82
	v_mov_b32_e32 v81, v83
	v_pk_add_f32 v[72:73], v[72:73], v[80:81]
	v_mul_f32_e32 v80, v45, v45
	v_mul_f32_e32 v82, v47, v47
	v_mul_f32_e32 v84, v58, v58
	v_mul_f32_e32 v85, v59, v59
	v_pk_fma_f32 v[80:81], v[44:45], v[44:45], v[80:81] op_sel_hi:[1,1,0]
	v_pk_fma_f32 v[82:83], v[46:47], v[46:47], v[82:83] op_sel_hi:[1,1,0]
	v_mov_b32_e32 v81, v84
	v_mov_b32_e32 v83, v85
	v_pk_add_f32 v[80:81], v[80:81], v[82:83]
	v_pk_mul_f32 v[82:83], v[0:1], v[0:1]
	v_pk_add_f32 v[72:73], v[72:73], v[80:81]
	v_pk_mul_f32 v[80:81], v[2:3], v[2:3]
	s_nop 0
	v_pk_mov_b32 v[84:85], v[82:83], v[80:81] op_sel:[1,0]
	v_mov_b32_e32 v83, v81
	v_pk_add_f32 v[80:81], v[84:85], v[82:83]
	v_pk_mul_f32 v[82:83], v[10:11], v[10:11]
	v_pk_mul_f32 v[84:85], v[8:9], v[8:9]
	v_pk_add_f32 v[80:81], v[80:81], v[80:81] op_sel:[0,1] op_sel_hi:[1,0]
	v_pk_mov_b32 v[86:87], v[84:85], v[82:83] op_sel:[1,0]
	v_mov_b32_e32 v85, v83
	v_pk_add_f32 v[82:83], v[86:87], v[84:85]
	v_mul_f32_e32 v84, v60, v60
	v_mul_f32_e32 v85, v61, v61
	v_pk_add_f32 v[82:83], v[82:83], v[82:83] op_sel:[0,1] op_sel_hi:[1,0]
	v_mov_b32_e32 v81, v84
	v_mov_b32_e32 v83, v85
	v_pk_add_f32 v[80:81], v[80:81], v[82:83]
	v_mul_f32_e32 v82, v33, v33
	v_mul_f32_e32 v84, v35, v35
	v_mul_f32_e32 v86, v62, v62
	v_mul_f32_e32 v87, v63, v63
	v_pk_fma_f32 v[82:83], v[32:33], v[32:33], v[82:83] op_sel_hi:[1,1,0]
	v_pk_fma_f32 v[84:85], v[34:35], v[34:35], v[84:85] op_sel_hi:[1,1,0]
	v_mov_b32_e32 v83, v86
	v_mov_b32_e32 v85, v87
	v_pk_add_f32 v[82:83], v[82:83], v[84:85]
	v_pk_add_f32 v[84:85], v[74:75], v[74:75] op_sel:[0,1] op_sel_hi:[1,0]
	v_pk_add_f32 v[80:81], v[80:81], v[82:83]
	v_mov_b32_e32 v82, v72
	v_mov_b32_e32 v83, v80
	v_mov_b32_e32 v80, v73
	s_nop 1
	v_mov_b32_e32 v72, v208
	v_mov_b32_e32 v73, v209
	v_mov_b32_e32 v74, v210
	v_mov_b32_e32 v75, v211
	v_pk_add_f32 v[80:81], v[82:83], v[80:81]
	v_mov_b32_e32 v85, v88
	ds_bpermute_b32 v83, v104, v81
	ds_bpermute_b32 v82, v104, v80
	v_pk_add_f32 v[78:79], v[78:79], v[84:85]
	v_mul_f32_e32 v84, v41, v41
	v_mul_f32_e32 v86, v43, v43
	v_pk_fma_f32 v[84:85], v[40:41], v[40:41], v[84:85] op_sel_hi:[1,1,0]
	v_pk_fma_f32 v[86:87], v[42:43], v[42:43], v[86:87] op_sel_hi:[1,1,0]
	v_mov_b32_e32 v85, v89
	v_mov_b32_e32 v87, v90
	v_pk_add_f32 v[84:85], v[84:85], v[86:87]
	s_waitcnt lgkmcnt(0)
; __device__ __forceinline__ void ew_post(const bf16* Y, const float* xin, float* xout, const float* gpost, const float* gnext, bf16* H, int gw, int ngw, int lane) {
;     ...
;             for (int q = 0; q < EW_NR; ++q) r2[q] = rsqrtf(wave_sum(s2[q]) * (1.f / DM) + RMS_EPS);
; #pragma unroll
;             for (int j = 0; j < 4; ++j) { const f32x4 g = *((const f32x4*)gnext + lane + 64 * j);
	v_pk_add_f32 v[80:81], v[80:81], v[82:83]
	v_pk_add_f32 v[78:79], v[78:79], v[84:85]
	v_mov_b32_e32 v84, v76
	v_mov_b32_e32 v85, v78
	v_mov_b32_e32 v78, v77
	ds_bpermute_b32 v83, v105, v81
	ds_bpermute_b32 v82, v105, v80
	v_pk_add_f32 v[76:77], v[84:85], v[78:79]
	ds_bpermute_b32 v79, v104, v77
	ds_bpermute_b32 v78, v104, v76
	s_waitcnt lgkmcnt(2)
	v_pk_add_f32 v[80:81], v[80:81], v[82:83]
	ds_bpermute_b32 v83, v106, v81
	ds_bpermute_b32 v82, v106, v80
	s_waitcnt lgkmcnt(2)
	v_pk_add_f32 v[76:77], v[76:77], v[78:79]
	ds_bpermute_b32 v79, v105, v77
	ds_bpermute_b32 v78, v105, v76
	s_waitcnt lgkmcnt(2)
	v_pk_add_f32 v[80:81], v[80:81], v[82:83]
	ds_bpermute_b32 v83, v107, v81
	ds_bpermute_b32 v82, v107, v80
	s_waitcnt lgkmcnt(2)
	v_pk_add_f32 v[76:77], v[76:77], v[78:79]
	ds_bpermute_b32 v79, v106, v77
	ds_bpermute_b32 v78, v106, v76
	s_waitcnt lgkmcnt(2)
	v_pk_add_f32 v[80:81], v[80:81], v[82:83]
	ds_bpermute_b32 v83, v108, v81
	ds_bpermute_b32 v82, v108, v80
	s_waitcnt lgkmcnt(2)
	v_pk_add_f32 v[76:77], v[76:77], v[78:79]
	ds_bpermute_b32 v79, v107, v77
	ds_bpermute_b32 v78, v107, v76
	s_waitcnt lgkmcnt(2)
	v_pk_add_f32 v[80:81], v[80:81], v[82:83]
	ds_bpermute_b32 v83, v109, v81
	ds_bpermute_b32 v82, v109, v80
	s_waitcnt lgkmcnt(2)
	v_pk_add_f32 v[76:77], v[76:77], v[78:79]
	ds_bpermute_b32 v79, v108, v77
	ds_bpermute_b32 v78, v108, v76
	s_waitcnt lgkmcnt(2)
	v_pk_add_f32 v[80:81], v[80:81], v[82:83]
	v_mov_b64_e32 v[82:83], s[24:25]
	v_pk_fma_f32 v[80:81], v[80:81], s[44:45], v[82:83] op_sel_hi:[1,0,0]
	s_waitcnt lgkmcnt(0)
	v_pk_add_f32 v[76:77], v[76:77], v[78:79]
	v_mul_f32_e32 v84, 0x4b800000, v81
	v_cmp_gt_f32_e32 vcc, s3, v81
	ds_bpermute_b32 v79, v109, v77
	ds_bpermute_b32 v78, v109, v76
	v_cndmask_b32_e32 v81, v81, v84, vcc
	v_rsq_f32_e32 v81, v81
	v_mul_f32_e32 v84, 0x4b800000, v80
	v_cmp_gt_f32_e64 s[4:5], s3, v80
	s_waitcnt lgkmcnt(0)
; __device__ __forceinline__ unsigned pk2(float lo, float hi) { f32v2 v = {lo, hi}; bf16v2 r = __builtin_convertvector(v, bf16v2); return __builtin_bit_cast(unsigned, r); }
; __device__ __forceinline__ void ew_post(const bf16* Y, const float* xin, float* xout, const float* gpost, const float* gnext, bf16* H, int gw, int ngw, int lane) {
;     ...
; #pragma unroll
;             for (int j = 0; j < 4; ++j) { const f32x4 g = *((const f32x4*)gnext + lane + 64 * j);
; #pragma unroll
;                 for (int q = 0; q < EW_NR; ++q) { v2u w; w.x = pk2(xv[q][j].x * r2[q] * g.x, xv[q][j].y * r2[q] * g.y); w.y = pk2(xv[q][j].z * r2[q] * g.z, xv[q][j].w * r2[q] * g.w);
;                     *((v2u*)(H + (size_t)(m0 + q) * DM) + lane + 64 * j) = w; } }
	v_pk_add_f32 v[76:77], v[76:77], v[78:79]
	v_cndmask_b32_e64 v80, v80, v84, s[4:5]
	v_rsq_f32_e32 v84, v80
	v_mul_f32_e32 v80, 0x45800000, v81
	v_pk_fma_f32 v[76:77], v[76:77], s[44:45], v[82:83] op_sel_hi:[1,0,0]
	v_cndmask_b32_e32 v80, v81, v80, vcc
	v_mul_f32_e32 v78, 0x4b800000, v77
	v_cmp_gt_f32_e32 vcc, s3, v77
	v_cmp_gt_f32_e64 s[6:7], s3, v76
	v_mul_f32_e32 v81, 0x45800000, v84
	v_cndmask_b32_e32 v77, v77, v78, vcc
	v_rsq_f32_e32 v77, v77
	v_mul_f32_e32 v78, 0x4b800000, v76
	v_cndmask_b32_e64 v76, v76, v78, s[6:7]
	v_rsq_f32_e32 v79, v76
	v_mul_f32_e32 v78, 0x45800000, v77
	v_pk_mul_f32 v[0:1], v[0:1], v[80:81] op_sel_hi:[1,0]
	v_pk_mul_f32 v[2:3], v[2:3], v[80:81] op_sel_hi:[1,0]
	v_cndmask_b32_e64 v76, v84, v81, s[4:5]
	v_cndmask_b32_e32 v78, v77, v78, vcc
	v_pk_mul_f32 v[0:1], v[0:1], v[72:73]
	v_pk_mul_f32 v[2:3], v[2:3], v[74:75]
	v_add_co_u32_e32 v84, vcc, s22, v68
	v_mul_f32_e32 v77, 0x45800000, v79
	v_cvt_pk_bf16_f32 v0, v0, v1
	v_cvt_pk_bf16_f32 v1, v2, v3
	v_addc_co_u32_e32 v85, vcc, -1, v69, vcc
	global_store_dwordx2 v[84:85], v[0:1], off offset:-3584
	v_pk_mul_f32 v[0:1], v[12:13], v[76:77] op_sel_hi:[1,0]
	v_pk_mul_f32 v[2:3], v[14:15], v[76:77] op_sel_hi:[1,0]
	v_pk_mul_f32 v[0:1], v[0:1], v[72:73]
	v_pk_mul_f32 v[2:3], v[2:3], v[74:75]
	v_cvt_pk_bf16_f32 v0, v0, v1
	v_cvt_pk_bf16_f32 v1, v2, v3
	global_store_dwordx2 v[84:85], v[0:1], off offset:-1536
	v_pk_mul_f32 v[0:1], v[16:17], v[78:79] op_sel_hi:[1,0]
	v_pk_mul_f32 v[2:3], v[18:19], v[78:79] op_sel_hi:[1,0]
	v_pk_mul_f32 v[0:1], v[72:73], v[0:1]
	v_pk_mul_f32 v[2:3], v[74:75], v[2:3]
	v_add_co_u32_e32 v12, vcc, s23, v68
	v_cndmask_b32_e64 v82, v79, v77, s[6:7]
	v_cvt_pk_bf16_f32 v0, v0, v1
	v_cvt_pk_bf16_f32 v1, v2, v3
	v_addc_co_u32_e32 v13, vcc, -1, v69, vcc
	global_store_dwordx2 v[12:13], v[0:1], off offset:-3584
	v_pk_mul_f32 v[0:1], v[4:5], v[82:83] op_sel_hi:[1,0]
	v_pk_mul_f32 v[2:3], v[6:7], v[82:83] op_sel_hi:[1,0]
	v_pk_mul_f32 v[0:1], v[72:73], v[0:1]
	v_pk_mul_f32 v[2:3], v[74:75], v[2:3]
	v_cvt_pk_bf16_f32 v0, v0, v1
	v_cvt_pk_bf16_f32 v1, v2, v3
	global_store_dwordx2 v[12:13], v[0:1], off offset:-1536
	s_nop 1
	v_mov_b32_e32 v0, v212
	v_mov_b32_e32 v1, v213
	v_mov_b32_e32 v2, v214
	v_mov_b32_e32 v3, v215
	v_pk_mul_f32 v[4:5], v[8:9], v[80:81] op_sel_hi:[1,0]
	v_pk_mul_f32 v[6:7], v[10:11], v[80:81] op_sel_hi:[1,0]
	v_pk_mul_f32 v[8:9], v[56:57], v[76:77] op_sel_hi:[1,0]
	v_pk_mul_f32 v[10:11], v[58:59], v[76:77] op_sel_hi:[1,0]
	v_pk_mul_f32 v[14:15], v[52:53], v[78:79] op_sel_hi:[1,0]
	v_pk_mul_f32 v[16:17], v[54:55], v[78:79] op_sel_hi:[1,0]
	v_pk_mul_f32 v[18:19], v[48:49], v[82:83] op_sel_hi:[1,0]
	v_pk_mul_f32 v[4:5], v[4:5], v[0:1]
	v_pk_mul_f32 v[6:7], v[6:7], v[2:3]
	v_cvt_pk_bf16_f32 v4, v4, v5
	v_cvt_pk_bf16_f32 v5, v6, v7
	global_store_dwordx2 v[84:85], v[4:5], off offset:-3072
	v_pk_mul_f32 v[4:5], v[20:21], v[76:77] op_sel_hi:[1,0]
	v_pk_mul_f32 v[6:7], v[22:23], v[76:77] op_sel_hi:[1,0]
	v_pk_mul_f32 v[4:5], v[4:5], v[0:1]
	v_pk_mul_f32 v[6:7], v[6:7], v[2:3]
	v_cvt_pk_bf16_f32 v4, v4, v5
	v_cvt_pk_bf16_f32 v5, v6, v7
	global_store_dwordx2 v[84:85], v[4:5], off offset:-1024
	v_pk_mul_f32 v[4:5], v[24:25], v[78:79] op_sel_hi:[1,0]
	v_pk_mul_f32 v[6:7], v[26:27], v[78:79] op_sel_hi:[1,0]
	v_pk_mul_f32 v[4:5], v[4:5], v[0:1]
	v_pk_mul_f32 v[6:7], v[6:7], v[2:3]
	v_cvt_pk_bf16_f32 v4, v4, v5
	v_cvt_pk_bf16_f32 v5, v6, v7
	global_store_dwordx2 v[12:13], v[4:5], off offset:-3072
	v_pk_mul_f32 v[4:5], v[28:29], v[82:83] op_sel_hi:[1,0]
	v_pk_mul_f32 v[6:7], v[34:35], v[80:81] op_sel_hi:[1,0]
	v_pk_mul_f32 v[0:1], v[0:1], v[4:5]
	v_pk_mul_f32 v[4:5], v[30:31], v[82:83] op_sel_hi:[1,0]
	v_cvt_pk_bf16_f32 v0, v0, v1
	v_pk_mul_f32 v[2:3], v[2:3], v[4:5]
	v_pk_mul_f32 v[4:5], v[32:33], v[80:81] op_sel_hi:[1,0]
	v_cvt_pk_bf16_f32 v1, v2, v3
	global_store_dwordx2 v[12:13], v[0:1], off offset:-1024
	s_nop 1
	v_mov_b32_e32 v0, v216
	v_mov_b32_e32 v1, v217
	v_mov_b32_e32 v2, v218
	v_mov_b32_e32 v3, v219
	v_pk_mul_f32 v[20:21], v[50:51], v[82:83] op_sel_hi:[1,0]
	v_pk_mul_f32 v[4:5], v[4:5], v[0:1]
	v_pk_mul_f32 v[6:7], v[6:7], v[2:3]
	v_cvt_pk_bf16_f32 v4, v4, v5
	v_cvt_pk_bf16_f32 v5, v6, v7
	global_store_dwordx2 v[84:85], v[4:5], off offset:-2560
	v_pk_mul_f32 v[4:5], v[44:45], v[76:77] op_sel_hi:[1,0]
	v_pk_mul_f32 v[6:7], v[46:47], v[76:77] op_sel_hi:[1,0]
	v_pk_mul_f32 v[4:5], v[4:5], v[0:1]
	v_pk_mul_f32 v[6:7], v[6:7], v[2:3]
	v_cvt_pk_bf16_f32 v4, v4, v5
	v_cvt_pk_bf16_f32 v5, v6, v7
	global_store_dwordx2 v[84:85], v[4:5], off offset:-512
	v_pk_mul_f32 v[4:5], v[40:41], v[78:79] op_sel_hi:[1,0]
	v_pk_mul_f32 v[6:7], v[42:43], v[78:79] op_sel_hi:[1,0]
	v_pk_mul_f32 v[4:5], v[4:5], v[0:1]
	v_pk_mul_f32 v[6:7], v[6:7], v[2:3]
	v_cvt_pk_bf16_f32 v4, v4, v5
	v_cvt_pk_bf16_f32 v5, v6, v7
	global_store_dwordx2 v[12:13], v[4:5], off offset:-2560
	v_pk_mul_f32 v[4:5], v[36:37], v[82:83] op_sel_hi:[1,0]
	v_pk_mul_f32 v[6:7], v[62:63], v[80:81] op_sel_hi:[1,0]
	v_pk_mul_f32 v[0:1], v[4:5], v[0:1]
	v_pk_mul_f32 v[4:5], v[38:39], v[82:83] op_sel_hi:[1,0]
	v_cvt_pk_bf16_f32 v0, v0, v1
	v_pk_mul_f32 v[2:3], v[4:5], v[2:3]
	v_pk_mul_f32 v[4:5], v[60:61], v[80:81] op_sel_hi:[1,0]
	v_cvt_pk_bf16_f32 v1, v2, v3
	global_store_dwordx2 v[12:13], v[0:1], off offset:-512
	s_nop 1
	v_mov_b32_e32 v0, v220
	v_mov_b32_e32 v1, v221
	v_mov_b32_e32 v2, v222
	v_mov_b32_e32 v3, v223
	v_pk_mul_f32 v[4:5], v[4:5], v[0:1]
	v_pk_mul_f32 v[6:7], v[6:7], v[2:3]
	v_pk_mul_f32 v[8:9], v[8:9], v[0:1]
	v_pk_mul_f32 v[10:11], v[10:11], v[2:3]
	v_pk_mul_f32 v[14:15], v[14:15], v[0:1]
	v_pk_mul_f32 v[16:17], v[16:17], v[2:3]
	v_pk_mul_f32 v[0:1], v[18:19], v[0:1]
	v_pk_mul_f32 v[2:3], v[20:21], v[2:3]
	v_cvt_pk_bf16_f32 v4, v4, v5
	v_cvt_pk_bf16_f32 v5, v6, v7
	v_cvt_pk_bf16_f32 v6, v8, v9
	v_cvt_pk_bf16_f32 v7, v10, v11
	v_cvt_pk_bf16_f32 v8, v14, v15
	v_cvt_pk_bf16_f32 v9, v16, v17
	v_cvt_pk_bf16_f32 v0, v0, v1
	v_cvt_pk_bf16_f32 v1, v2, v3
	global_store_dwordx2 v[84:85], v[4:5], off offset:-2048
	global_store_dwordx2 v[12:13], v[6:7], off offset:-4096
	global_store_dwordx2 v[12:13], v[8:9], off offset:-2048
	global_store_dwordx2 v[12:13], v[0:1], off
	s_branch .LBB0_190

; __device__ __forceinline__ void ew_post(const bf16* Y, const float* xin, float* xout, const float* gpost, const float* gnext, bf16* H, int gw, int ngw, int lane) {
;     for (int m0 = EW_NR * gw; m0 < NTOK; m0 += EW_NR * ngw) {
;         f32x4 y[EW_NR][4], xv[EW_NR][4]; float s[EW_NR];
; #pragma unroll
;         for (int q = 0; q < EW_NR; ++q) { const v2u* yr = (const v2u*)(Y + (size_t)(m0 + q) * DM) + lane; const f32x4* xr = (const f32x4*)(xin + (size_t)(m0 + q) * DM) + lane;
; #pragma unroll
;             for (int j = 0; j < 4; ++j) { const v2u w = __builtin_nontemporal_load(yr + 64 * j); y[q][j] = (f32x4){bf_lo(w.x), bf_hi(w.x), bf_lo(w.y), bf_hi(w.y)}; xv[q][j] = __builtin_nontemporal_load(xr + 64 * j); } }
; #pragma unroll
;         for (int q = 0; q < EW_NR; ++q) { s[q] = 0.f;
; #pragma unroll
;             for (int j = 0; j < 4; ++j) s[q] += (y[q][j].x * y[q][j].x + y[q][j].y * y[q][j].y) + (y[q][j].z * y[q][j].z + y[q][j].w * y[q][j].w); }
;         float rstd[EW_NR], s2[EW_NR];
; #pragma unroll
;         for (int q = 0; q < EW_NR; ++q) { rstd[q] = rsqrtf(wave_sum(s[q]) * (1.f / DM) + RMS_EPS); s2[q] = 0.f; }
; __global__ void __launch_bounds__(NTHREADS, 2) fwd_megakernel(Args A) {
;     ...
;             ew_post(Y, l == 0 ? A.in[0] : xres, xres, A.in[12] + (size_t)l * DM, A.in[13] + (size_t)l * DM, H, gw, ngw, lane);
.LBB0_204:
	s_and_b64 vcc, exec, s[4:5]
	s_cbranch_vccz .LBB0_211
	v_readlane_b32 s16, v254, 15
	s_cmp_gt_i32 s73, 6
	v_readlane_b32 s17, v254, 16
	s_mov_b32 s20, 0xfbfff000
	s_brev_b32 s21, 63
	s_movk_i32 s22, 0x1000
	s_movk_i32 s23, 0x2000
	s_movk_i32 s24, 0x3000
	s_cbranch_scc0 .LBB0_569
	s_cmpk_gt_i32 s96, 0x1fff
	s_cbranch_scc1 .LBB0_570
	v_and_b32_e32 v0, 64, v226
	v_add_u32_e32 v0, 64, v0
	v_xor_b32_e32 v1, 1, v226
	v_cmp_lt_i32_e32 vcc, v1, v0
	s_ashr_i32 s89, s88, 31
	v_readlane_b32 s56, v253, 30
	v_cndmask_b32_e32 v1, v226, v1, vcc
	v_lshlrev_b32_e32 v130, 2, v1
	v_xor_b32_e32 v1, 2, v226
	v_cmp_lt_i32_e32 vcc, v1, v0
	s_lshl_b64 s[4:5], s[88:89], 12
	v_readlane_b32 s66, v253, 40
	v_cndmask_b32_e32 v1, v226, v1, vcc
	v_lshlrev_b32_e32 v131, 2, v1
	v_xor_b32_e32 v1, 4, v226
	v_cmp_lt_i32_e32 vcc, v1, v0
	v_readlane_b32 s67, v253, 41
	s_add_u32 s6, s66, s4
	v_cndmask_b32_e32 v1, v226, v1, vcc
	v_lshlrev_b32_e32 v132, 2, v1
	v_xor_b32_e32 v1, 8, v226
	v_readlane_b32 s64, v253, 38
	s_addc_u32 s7, s67, s5
	v_cmp_lt_i32_e32 vcc, v1, v0
	v_readlane_b32 s57, v253, 31
	v_readlane_b32 s58, v253, 32
	v_readlane_b32 s59, v253, 33
	v_readlane_b32 s60, v253, 34
	v_readlane_b32 s61, v253, 35
	v_readlane_b32 s62, v253, 36
	v_readlane_b32 s63, v253, 37
	v_readlane_b32 s65, v253, 39
	v_readlane_b32 s68, v253, 42
	v_readlane_b32 s69, v253, 43
	v_readlane_b32 s70, v253, 44
	v_readlane_b32 s71, v253, 45
	s_add_u32 s4, s64, s4
	v_cndmask_b32_e32 v1, v226, v1, vcc
	s_addc_u32 s5, s65, s5
	v_readlane_b32 s56, v254, 25
	v_lshlrev_b32_e32 v133, 2, v1
	v_xor_b32_e32 v1, 16, v226
	s_cmp_eq_u32 s88, 0
	v_readlane_b32 s57, v254, 26
	v_cmp_lt_i32_e32 vcc, v1, v0
	s_cselect_b32 s13, s57, s79
	s_cselect_b32 s12, s56, s78
	s_lshl_b32 s8, s96, 2
	v_cndmask_b32_e32 v1, v226, v1, vcc
	v_lshlrev_b32_e32 v134, 2, v1
	v_xor_b32_e32 v1, 32, v226
	v_lshlrev_b32_e32 v178, 4, v184
	s_ashr_i32 s9, s8, 31
	v_cmp_lt_i32_e32 vcc, v1, v0
	v_lshl_add_u64 v[68:69], s[4:5], 0, v[178:179]
	v_lshl_add_u64 v[70:71], s[6:7], 0, v[178:179]
	s_lshl_b64 s[4:5], s[8:9], 11
	v_readlane_b32 s6, v254, 11
	v_cndmask_b32_e32 v0, v226, v1, vcc
	s_add_u32 s4, s6, s4
	v_readlane_b32 s6, v254, 12
	v_lshlrev_b32_e32 v135, 2, v0
	v_lshlrev_b32_e32 v0, 3, v184
	v_mov_b32_e32 v1, v179
	s_addc_u32 s5, s6, s5
	v_lshl_add_u64 v[72:73], s[4:5], 0, v[0:1]
	s_lshl_b64 s[4:5], s[8:9], 12
	s_add_u32 s10, s78, s4
	v_readlane_b32 s60, v254, 29
	v_readlane_b32 s61, v254, 30
	v_readlane_b32 s68, v254, 37
	v_readlane_b32 s69, v254, 38
	v_readlane_b32 s70, v254, 39
	v_readlane_b32 s71, v254, 40
	s_addc_u32 s11, s79, s5
	v_readlane_b32 s63, v254, 32
	v_readlane_b32 s66, v254, 35
	v_readlane_b32 s67, v254, 36
	v_readlane_b32 s60, v255, 2
	v_readlane_b32 s46, v255, 0
	v_readlane_b32 s42, v254, 62
	v_readlane_b32 s70, v254, 57
	v_readlane_b32 s68, v254, 55
	s_add_u32 s12, s12, s4
	v_readlane_b32 s89, v255, 8
	v_readlane_b32 s61, v255, 3
	v_readlane_b32 s47, v255, 1
	v_readlane_b32 s43, v254, 63
	v_readlane_b32 s14, v254, 13
	v_readlane_b32 s63, v254, 59
	v_readlane_b32 s71, v254, 58
	v_readlane_b32 s69, v254, 56
	v_readlane_b32 s66, v254, 53
	s_mov_b32 s26, 0x358637bd
	s_addc_u32 s13, s13, s5
	v_readlane_b32 s58, v254, 27
	v_readlane_b32 s59, v254, 28
	v_readlane_b32 s62, v254, 31
	v_readlane_b32 s64, v254, 33
	v_readlane_b32 s65, v254, 34
	v_readlane_b32 s15, v254, 14
	v_readlane_b32 s67, v254, 54
	global_load_dwordx4 v[156:159], v[68:69], off
	global_load_dwordx4 v[160:163], v[68:69], off offset:1024
	global_load_dwordx4 v[164:167], v[68:69], off offset:2048
	global_load_dwordx4 v[168:171], v[68:69], off offset:3072
	s_and_b64 vcc, exec, s[30:31]
	s_cbranch_vccz .Lewa_nogn
	global_load_dwordx4 v[232:235], v[70:71], off
	global_load_dwordx4 v[236:239], v[70:71], off offset:1024
	global_load_dwordx4 v[240:243], v[70:71], off offset:2048
	global_load_dwordx4 v[244:247], v[70:71], off offset:3072

; __device__ __forceinline__ void ew_post(const bf16* Y, const float* xin, float* xout, const float* gpost, const float* gnext, bf16* H, int gw, int ngw, int lane) {
;     for (int m0 = EW_NR * gw; m0 < NTOK; m0 += EW_NR * ngw) {
;         f32x4 y[EW_NR][4], xv[EW_NR][4]; float s[EW_NR];
; #pragma unroll
;         for (int q = 0; q < EW_NR; ++q) { const v2u* yr = (const v2u*)(Y + (size_t)(m0 + q) * DM) + lane; const f32x4* xr = (const f32x4*)(xin + (size_t)(m0 + q) * DM) + lane;
; #pragma unroll
;             for (int j = 0; j < 4; ++j) { const v2u w = __builtin_nontemporal_load(yr + 64 * j); y[q][j] = (f32x4){bf_lo(w.x), bf_hi(w.x), bf_lo(w.y), bf_hi(w.y)}; xv[q][j] = __builtin_nontemporal_load(xr + 64 * j); } }
; #pragma unroll
;         for (int q = 0; q < EW_NR; ++q) { s[q] = 0.f;
; #pragma unroll
;             for (int j = 0; j < 4; ++j) s[q] += (y[q][j].x * y[q][j].x + y[q][j].y * y[q][j].y) + (y[q][j].z * y[q][j].z + y[q][j].w * y[q][j].w); }
.LBB0_209:
	v_add_co_u32_e32 v8, vcc, 0xfffff000, v72
	global_load_dwordx2 v[38:39], v[72:73], off offset:-4096 nt
	global_load_dwordx2 v[40:41], v[72:73], off offset:-2048 nt
	v_addc_co_u32_e32 v9, vcc, -1, v73, vcc
	global_load_dwordx2 v[42:43], v[72:73], off nt
	global_load_dwordx2 v[48:49], v[8:9], off offset:-2048 nt
	global_load_dwordx2 v[50:51], v[8:9], off offset:-3584 nt
	global_load_dwordx2 v[52:53], v[8:9], off offset:-3072 nt
	global_load_dwordx2 v[54:55], v[8:9], off offset:-2560 nt
	v_lshl_add_u64 v[10:11], s[12:13], 0, v[178:179]
	global_load_dwordx2 v[96:97], v[72:73], off offset:-3584 nt
	global_load_dwordx2 v[106:107], v[72:73], off offset:-3072 nt
	global_load_dwordx2 v[98:99], v[72:73], off offset:-2560 nt
	global_load_dwordx2 v[108:109], v[72:73], off offset:-1536 nt
	global_load_dwordx2 v[66:67], v[72:73], off offset:-1024 nt
	global_load_dwordx2 v[46:47], v[72:73], off offset:-512 nt
	global_load_dwordx2 v[90:91], v[8:9], off offset:-1536 nt
	global_load_dwordx4 v[20:23], v[10:11], off nt
	global_load_dwordx4 v[12:15], v[10:11], off offset:1024 nt
	global_load_dwordx4 v[4:7], v[10:11], off offset:2048 nt
	global_load_dwordx4 v[0:3], v[10:11], off offset:3072 nt
	global_load_dwordx2 v[92:93], v[8:9], off offset:-1024 nt
	global_load_dwordx2 v[104:105], v[8:9], off offset:-512 nt
	v_add_co_u32_e64 v36, s[4:5], s24, v10
	v_add_co_u32_e32 v44, vcc, s22, v10
	s_nop 0
	v_addc_co_u32_e64 v37, s[4:5], 0, v11, s[4:5]
	s_mov_b64 s[4:5], vcc
	v_add_co_u32_e32 v64, vcc, s23, v10
	v_addc_co_u32_e64 v45, s[4:5], 0, v11, s[4:5]
	global_load_dwordx4 v[28:31], v[36:37], off nt
	v_addc_co_u32_e32 v65, vcc, 0, v11, vcc
	global_load_dwordx4 v[16:19], v[44:45], off offset:1024 nt
	global_load_dwordx4 v[8:11], v[44:45], off offset:2048 nt
	global_load_dwordx4 v[24:27], v[64:65], off offset:-4096 nt
	global_load_dwordx4 v[32:35], v[64:65], off nt
	s_nop 1
	v_mov_b32_e32 v136, v156
	v_mov_b32_e32 v137, v157
	v_mov_b32_e32 v138, v158
	v_mov_b32_e32 v139, v159
	v_mov_b64_e32 v[148:149], s[26:27]
	global_load_dwordx4 v[192:195], v[44:45], off offset:3072 nt
	global_load_dwordx4 v[196:199], v[64:65], off offset:1024 nt
	global_load_dwordx4 v[200:203], v[64:65], off offset:2048 nt
	global_load_dwordx4 v[204:207], v[64:65], off offset:3072 nt
	global_load_dwordx4 v[208:211], v[36:37], off offset:1024 nt
	global_load_dwordx4 v[212:215], v[36:37], off offset:2048 nt
	global_load_dwordx4 v[216:219], v[36:37], off offset:3072 nt
	s_waitcnt vmcnt(0)
	v_and_b32_e32 v121, 0xffff0000, v97
	v_and_b32_e32 v119, 0xffff0000, v96
	v_lshlrev_b32_e32 v120, 16, v97
	v_lshlrev_b32_e32 v118, 16, v96
	v_lshlrev_b32_e32 v59, 16, v38
	v_lshlrev_b32_e32 v77, 16, v40
	v_lshlrev_b32_e32 v87, 16, v48
	v_and_b32_e32 v101, 0xffff0000, v50
	v_and_b32_e32 v103, 0xffff0000, v51
	v_and_b32_e32 v75, 0xffff0000, v40
	v_lshlrev_b32_e32 v78, 16, v41
	v_and_b32_e32 v79, 0xffff0000, v41
	v_lshlrev_b32_e32 v83, 16, v42
	v_and_b32_e32 v81, 0xffff0000, v42
	v_lshlrev_b32_e32 v84, 16, v43
	v_and_b32_e32 v85, 0xffff0000, v43
	v_and_b32_e32 v63, 0xffff0000, v48
	v_lshlrev_b32_e32 v88, 16, v49
	v_and_b32_e32 v89, 0xffff0000, v49
	v_lshlrev_b32_e32 v100, 16, v50
	v_lshlrev_b32_e32 v102, 16, v51
	v_and_b32_e32 v41, 0xffff0000, v53
	v_and_b32_e32 v40, 0xffff0000, v52
	v_lshlrev_b32_e32 v48, 16, v54
	v_and_b32_e32 v49, 0xffff0000, v54
	v_mul_f32_e32 v42, v103, v103
	v_mul_f32_e32 v54, v101, v101
	v_mov_b32_e32 v43, v87
	v_and_b32_e32 v57, 0xffff0000, v38
	v_lshlrev_b32_e32 v60, 16, v39
	v_and_b32_e32 v61, 0xffff0000, v39
	v_lshlrev_b32_e32 v39, 16, v53
	v_lshlrev_b32_e32 v38, 16, v52
	v_lshlrev_b32_e32 v50, 16, v55
	v_and_b32_e32 v51, 0xffff0000, v55
	v_pk_mul_f32 v[52:53], v[40:41], v[40:41]
	v_pk_fma_f32 v[94:95], v[102:103], v[102:103], v[42:43] op_sel_hi:[1,1,0]
	v_pk_fma_f32 v[54:55], v[100:101], v[100:101], v[54:55] op_sel_hi:[1,1,0]
	v_pk_fma_f32 v[52:53], v[38:39], v[38:39], v[52:53]
	v_mov_b32_e32 v86, v54
	v_mov_b32_e32 v42, v94
	v_mul_f32_e32 v56, v63, v63
	v_pk_add_f32 v[54:55], v[54:55], v[94:95]
	v_pk_add_f32 v[52:53], v[52:53], v[52:53] op_sel:[0,1] op_sel_hi:[1,0]
	v_pk_mul_f32 v[42:43], v[86:87], v[42:43]
	v_mov_b32_e32 v53, v56
	v_mov_b32_e32 v55, v43
	v_pk_add_f32 v[42:43], v[54:55], v[52:53]
	v_mul_f32_e32 v52, v49, v49
	v_mul_f32_e32 v54, v51, v51
	v_mul_f32_e32 v58, v88, v88
	v_mul_f32_e32 v62, v89, v89
	v_pk_fma_f32 v[52:53], v[48:49], v[48:49], v[52:53] op_sel_hi:[1,1,0]
	v_pk_fma_f32 v[54:55], v[50:51], v[50:51], v[54:55] op_sel_hi:[1,1,0]
	v_mov_b32_e32 v53, v58
	v_mov_b32_e32 v55, v62
	v_pk_add_f32 v[52:53], v[52:53], v[54:55]
	v_and_b32_e32 v113, 0xffff0000, v91
	v_pk_add_f32 v[52:53], v[42:43], v[52:53]
	v_and_b32_e32 v111, 0xffff0000, v90
	v_lshlrev_b32_e32 v112, 16, v91
	v_mul_f32_e32 v42, v113, v113
	v_and_b32_e32 v95, 0xffff0000, v93
	v_and_b32_e32 v94, 0xffff0000, v92
	v_lshlrev_b32_e32 v110, 16, v90
	v_pk_fma_f32 v[54:55], v[112:113], v[112:113], v[42:43] op_sel_hi:[1,1,0]
	v_lshlrev_b32_e32 v43, 16, v93
	v_lshlrev_b32_e32 v42, 16, v92
	v_pk_mul_f32 v[90:91], v[94:95], v[94:95]
	v_mul_f32_e32 v56, v111, v111
	v_pk_fma_f32 v[114:115], v[42:43], v[42:43], v[90:91]
	v_lshlrev_b32_e32 v90, 16, v104
	v_and_b32_e32 v91, 0xffff0000, v104
	v_lshlrev_b32_e32 v92, 16, v105
	v_and_b32_e32 v93, 0xffff0000, v105
	v_pk_fma_f32 v[104:105], v[110:111], v[110:111], v[56:57] op_sel_hi:[1,1,0]
	v_mov_b32_e32 v116, v54
	v_mov_b32_e32 v58, v104
	v_mov_b32_e32 v117, v59
	v_pk_add_f32 v[54:55], v[104:105], v[54:55]
	v_pk_mul_f32 v[104:105], v[58:59], v[116:117]
	v_mul_f32_e32 v62, v57, v57
	v_mov_b32_e32 v55, v105
	v_pk_add_f32 v[104:105], v[114:115], v[114:115] op_sel:[0,1] op_sel_hi:[1,0]
	v_mul_f32_e32 v56, v91, v91
	v_mov_b32_e32 v105, v62
	v_pk_add_f32 v[54:55], v[54:55], v[104:105]
	v_pk_fma_f32 v[104:105], v[90:91], v[90:91], v[56:57] op_sel_hi:[1,1,0]
	v_mul_f32_e32 v56, v93, v93
	v_mul_f32_e32 v74, v60, v60
	v_mul_f32_e32 v76, v61, v61
	v_pk_fma_f32 v[114:115], v[92:93], v[92:93], v[56:57] op_sel_hi:[1,1,0]
	v_mov_b32_e32 v105, v74
	v_mov_b32_e32 v115, v76
	v_pk_add_f32 v[104:105], v[104:105], v[114:115]
	v_mov_b32_e32 v143, v52
	v_pk_add_f32 v[54:55], v[54:55], v[104:105]
	v_mul_f32_e32 v56, v121, v121
	v_mov_b32_e32 v142, v54
	v_mov_b32_e32 v52, v55
	v_pk_add_f32 v[52:53], v[142:143], v[52:53]
	ds_bpermute_b32 v55, v130, v53
	ds_bpermute_b32 v54, v130, v52
	v_pk_fma_f32 v[114:115], v[120:121], v[120:121], v[56:57] op_sel_hi:[1,1,0]
	v_lshlrev_b32_e32 v105, 16, v107
	v_lshlrev_b32_e32 v104, 16, v106
	v_and_b32_e32 v107, 0xffff0000, v107
	v_and_b32_e32 v106, 0xffff0000, v106
	v_mul_f32_e32 v56, v119, v119
	v_pk_mul_f32 v[96:97], v[106:107], v[106:107]
	v_pk_fma_f32 v[122:123], v[118:119], v[118:119], v[56:57] op_sel_hi:[1,1,0]
	s_waitcnt lgkmcnt(0)
; __device__ __forceinline__ void ew_post(const bf16* Y, const float* xin, float* xout, const float* gpost, const float* gnext, bf16* H, int gw, int ngw, int lane) {
;     ...
;         for (int q = 0; q < EW_NR; ++q) { s[q] = 0.f;
; #pragma unroll
;             for (int j = 0; j < 4; ++j) s[q] += (y[q][j].x * y[q][j].x + y[q][j].y * y[q][j].y) + (y[q][j].z * y[q][j].z + y[q][j].w * y[q][j].w); }
;         float rstd[EW_NR], s2[EW_NR];
; #pragma unroll
;         for (int q = 0; q < EW_NR; ++q) { rstd[q] = rsqrtf(wave_sum(s[q]) * (1.f / DM) + RMS_EPS); s2[q] = 0.f; }
; #pragma unroll
;         for (int j = 0; j < 4; ++j) { const f32x4 g = *((const f32x4*)gpost + lane + 64 * j);
	v_pk_add_f32 v[52:53], v[52:53], v[54:55]
	v_pk_fma_f32 v[116:117], v[104:105], v[104:105], v[96:97]
	v_mov_b32_e32 v76, v122
	v_mov_b32_e32 v124, v114
	v_mov_b32_e32 v125, v77
	ds_bpermute_b32 v55, v131, v53
	ds_bpermute_b32 v54, v131, v52
	v_and_b32_e32 v97, 0xffff0000, v98
	v_mul_f32_e32 v58, v75, v75
	v_pk_add_f32 v[114:115], v[122:123], v[114:115]
	v_pk_mul_f32 v[122:123], v[76:77], v[124:125]
	v_pk_add_f32 v[116:117], v[116:117], v[116:117] op_sel:[0,1] op_sel_hi:[1,0]
	v_lshlrev_b32_e32 v96, 16, v98
	v_lshlrev_b32_e32 v98, 16, v99
	v_and_b32_e32 v99, 0xffff0000, v99
	v_mov_b32_e32 v115, v123
	v_mov_b32_e32 v117, v58
	v_mul_f32_e32 v56, v97, v97
	v_pk_add_f32 v[114:115], v[114:115], v[116:117]
	v_pk_fma_f32 v[116:117], v[96:97], v[96:97], v[56:57] op_sel_hi:[1,1,0]
	v_mul_f32_e32 v56, v99, v99
	v_mul_f32_e32 v62, v78, v78
	v_mul_f32_e32 v74, v79, v79
	v_pk_fma_f32 v[122:123], v[98:99], v[98:99], v[56:57] op_sel_hi:[1,1,0]
	v_mov_b32_e32 v117, v62
	v_mov_b32_e32 v123, v74
	s_waitcnt lgkmcnt(0)
	v_pk_add_f32 v[52:53], v[52:53], v[54:55]
	v_pk_add_f32 v[116:117], v[116:117], v[122:123]
	v_and_b32_e32 v123, 0xffff0000, v108
	v_and_b32_e32 v125, 0xffff0000, v109
	ds_bpermute_b32 v55, v132, v53
	ds_bpermute_b32 v54, v132, v52
	v_pk_add_f32 v[128:129], v[114:115], v[116:117]
	v_lshlrev_b32_e32 v122, 16, v108
	v_lshlrev_b32_e32 v124, 16, v109
	v_mul_f32_e32 v56, v125, v125
	v_and_b32_e32 v117, 0xffff0000, v67
	v_and_b32_e32 v116, 0xffff0000, v66
	v_lshlrev_b32_e32 v108, 16, v46
	v_and_b32_e32 v109, 0xffff0000, v46
	v_mul_f32_e32 v46, v123, v123
	v_pk_fma_f32 v[140:141], v[124:125], v[124:125], v[56:57] op_sel_hi:[1,1,0]
	v_lshlrev_b32_e32 v115, 16, v67
	v_lshlrev_b32_e32 v114, 16, v66
	v_pk_mul_f32 v[66:67], v[116:117], v[116:117]
	v_lshlrev_b32_e32 v126, 16, v47
	v_and_b32_e32 v127, 0xffff0000, v47
	v_pk_fma_f32 v[46:47], v[122:123], v[122:123], v[46:47] op_sel_hi:[1,1,0]
	v_pk_fma_f32 v[66:67], v[114:115], v[114:115], v[66:67]
	v_mov_b32_e32 v82, v46
	v_mov_b32_e32 v142, v140
	v_mov_b32_e32 v143, v83
	v_mul_f32_e32 v56, v81, v81
	v_pk_add_f32 v[46:47], v[46:47], v[140:141]
	v_pk_mul_f32 v[140:141], v[82:83], v[142:143]
	v_pk_add_f32 v[66:67], v[66:67], v[66:67] op_sel:[0,1] op_sel_hi:[1,0]
	v_mov_b32_e32 v47, v141
	v_mov_b32_e32 v67, v56
	v_mul_f32_e32 v56, v109, v109
	s_waitcnt lgkmcnt(0)
	v_pk_add_f32 v[52:53], v[52:53], v[54:55]
	v_pk_add_f32 v[46:47], v[46:47], v[66:67]
	v_pk_fma_f32 v[66:67], v[108:109], v[108:109], v[56:57] op_sel_hi:[1,1,0]
	v_mul_f32_e32 v56, v127, v127
	ds_bpermute_b32 v55, v133, v53
	ds_bpermute_b32 v54, v133, v52
	v_mul_f32_e32 v58, v84, v84
	v_mul_f32_e32 v62, v85, v85
	v_pk_fma_f32 v[140:141], v[126:127], v[126:127], v[56:57] op_sel_hi:[1,1,0]
	v_mov_b32_e32 v67, v58
	v_mov_b32_e32 v141, v62
	v_pk_add_f32 v[66:67], v[66:67], v[140:141]
	v_mov_b32_e32 v74, v77
	v_pk_add_f32 v[46:47], v[46:47], v[66:67]
	s_waitcnt lgkmcnt(0)
	v_pk_add_f32 v[66:67], v[52:53], v[54:55]
	v_mov_b32_e32 v52, v46
	v_mov_b32_e32 v53, v128
	v_mov_b32_e32 v128, v47
	ds_bpermute_b32 v141, v134, v67
	ds_bpermute_b32 v140, v134, v66
	v_pk_add_f32 v[46:47], v[52:53], v[128:129]
	ds_bpermute_b32 v129, v130, v47
	ds_bpermute_b32 v128, v130, v46
	s_nop 1
	v_mov_b32_e32 v52, v192
	v_mov_b32_e32 v53, v193
	v_mov_b32_e32 v54, v194
	v_mov_b32_e32 v55, v195
	s_waitcnt lgkmcnt(2)
	v_pk_add_f32 v[44:45], v[66:67], v[140:141]
	ds_bpermute_b32 v67, v135, v45
	ds_bpermute_b32 v66, v135, v44
	s_waitcnt lgkmcnt(2)
	v_pk_add_f32 v[46:47], v[46:47], v[128:129]
	ds_bpermute_b32 v129, v131, v47
	ds_bpermute_b32 v128, v131, v46
	s_nop 1
	v_mov_b32_e32 v140, v196
	v_mov_b32_e32 v141, v197
	v_mov_b32_e32 v142, v198
	v_mov_b32_e32 v143, v199
	s_waitcnt lgkmcnt(2)
	v_pk_add_f32 v[44:45], v[44:45], v[66:67]
	v_mov_b32_e32 v80, v83
	v_pk_fma_f32 v[150:151], v[44:45], s[44:45], v[148:149] op_sel_hi:[1,0,0]
	s_waitcnt lgkmcnt(0)
	v_pk_add_f32 v[44:45], v[46:47], v[128:129]
	ds_bpermute_b32 v47, v132, v45
	ds_bpermute_b32 v46, v132, v44
	v_mul_f32_e32 v56, 0x4b800000, v151
	v_cmp_gt_f32_e32 vcc, s3, v151
	s_waitcnt lgkmcnt(0)
	v_pk_add_f32 v[128:129], v[44:45], v[46:47]
	ds_bpermute_b32 v145, v133, v129
	ds_bpermute_b32 v144, v133, v128
	v_cndmask_b32_e32 v56, v151, v56, vcc
	v_rsq_f32_e32 v56, v56
	s_nop 1
	v_mov_b32_e32 v44, v200
	v_mov_b32_e32 v45, v201
	v_mov_b32_e32 v46, v202
	v_mov_b32_e32 v47, v203
	s_nop 0
	s_nop 1
	v_mov_b32_e32 v64, v204
	v_mov_b32_e32 v65, v205
	v_mov_b32_e32 v66, v206
	v_mov_b32_e32 v67, v207
	s_waitcnt lgkmcnt(0)
	v_pk_add_f32 v[128:129], v[128:129], v[144:145]
	ds_bpermute_b32 v153, v134, v129
	ds_bpermute_b32 v152, v134, v128
	v_mul_f32_e32 v58, 0x45800000, v56
	v_cndmask_b32_e32 v56, v56, v58, vcc
	v_mul_f32_e32 v58, 0x4b800000, v150
	v_cmp_gt_f32_e32 vcc, s3, v150
	s_waitcnt lgkmcnt(0)
	v_pk_add_f32 v[128:129], v[128:129], v[152:153]
	ds_bpermute_b32 v153, v135, v129
	ds_bpermute_b32 v152, v135, v128
	v_cndmask_b32_e32 v58, v150, v58, vcc
	v_rsq_f32_e32 v58, v58
	v_pk_mul_f32 v[100:101], v[56:57], v[100:101] op_sel_hi:[0,1]
	v_pk_mul_f32 v[102:103], v[56:57], v[102:103] op_sel_hi:[0,1]
	s_waitcnt lgkmcnt(0)
; __device__ __forceinline__ void ew_post(const bf16* Y, const float* xin, float* xout, const float* gpost, const float* gnext, bf16* H, int gw, int ngw, int lane) {
;     ...
; #pragma unroll
;         for (int j = 0; j < 4; ++j) { const f32x4 g = *((const f32x4*)gpost + lane + 64 * j);
; #pragma unroll
;             for (int q = 0; q < EW_NR; ++q) { xv[q][j] = xv[q][j] + y[q][j] * rstd[q] * g; __builtin_nontemporal_store(xv[q][j], (f32x4*)(xout + (size_t)(m0 + q) * DM) + lane + 64 * j);
;                 s2[q] += (xv[q][j].x * xv[q][j].x + xv[q][j].y * xv[q][j].y) + (xv[q][j].z * xv[q][j].z + xv[q][j].w * xv[q][j].w); } }
	v_pk_add_f32 v[128:129], v[128:129], v[152:153]
	v_pk_fma_f32 v[22:23], v[102:103], v[138:139], v[22:23]
	v_pk_fma_f32 v[128:129], v[128:129], s[44:45], v[148:149] op_sel_hi:[1,0,0]
	v_pk_fma_f32 v[20:21], v[100:101], v[136:137], v[20:21]
	v_mul_f32_e32 v62, 0x4b800000, v129
	v_cmp_gt_f32_e64 s[4:5], s3, v129
	s_nop 1
	v_mov_b32_e32 v100, v208
	v_mov_b32_e32 v101, v209
	v_mov_b32_e32 v102, v210
	v_mov_b32_e32 v103, v211
	s_nop 1
	v_mov_b32_e32 v144, v212
	v_mov_b32_e32 v145, v213
	v_mov_b32_e32 v146, v214
	v_mov_b32_e32 v147, v215
	v_cndmask_b32_e64 v62, v129, v62, s[4:5]
	v_rsq_f32_e32 v62, v62
	s_nop 1
	v_mov_b32_e32 v148, v216
	v_mov_b32_e32 v149, v217
	v_mov_b32_e32 v150, v218
	v_mov_b32_e32 v151, v219
	v_mul_f32_e32 v36, 0x45800000, v58
	v_cndmask_b32_e32 v58, v58, v36, vcc
	v_mul_f32_e32 v36, 0x45800000, v62
	v_cndmask_b32_e64 v76, v62, v36, s[4:5]
	v_mul_f32_e32 v36, 0x4b800000, v128
	v_cmp_gt_f32_e32 vcc, s3, v128
	v_pk_mul_f32 v[50:51], v[56:57], v[50:51] op_sel_hi:[0,1]
	v_pk_mul_f32 v[48:49], v[56:57], v[48:49] op_sel_hi:[0,1]
	v_cndmask_b32_e32 v36, v128, v36, vcc
	v_rsq_f32_e32 v62, v36
	v_pk_mul_f32 v[36:37], v[58:59], v[110:111] op_sel_hi:[0,1]
	v_pk_fma_f32 v[24:25], v[36:37], v[136:137], v[24:25]
	v_lshl_add_u64 v[128:129], s[10:11], 0, v[178:179]
	v_mul_f32_e32 v36, 0x45800000, v62
	v_pk_mul_f32 v[110:111], v[58:59], v[112:113] op_sel_hi:[0,1]
	v_cndmask_b32_e32 v82, v62, v36, vcc
	v_pk_mul_f32 v[36:37], v[76:77], v[118:119] op_sel_hi:[0,1]
	v_add_co_u32_e32 v118, vcc, s23, v128
	v_pk_fma_f32 v[26:27], v[110:111], v[138:139], v[26:27]
	v_pk_mul_f32 v[110:111], v[76:77], v[120:121] op_sel_hi:[0,1]
	v_addc_co_u32_e32 v119, vcc, 0, v129, vcc
	v_pk_fma_f32 v[34:35], v[138:139], v[110:111], v[34:35]
	v_pk_fma_f32 v[32:33], v[136:137], v[36:37], v[32:33]
	v_pk_mul_f32 v[36:37], v[82:83], v[122:123] op_sel_hi:[0,1]
	v_pk_mul_f32 v[110:111], v[82:83], v[124:125] op_sel_hi:[0,1]
	v_add_co_u32_e32 v120, vcc, s24, v128
	v_pk_fma_f32 v[30:31], v[138:139], v[110:111], v[30:31]
	v_pk_fma_f32 v[28:29], v[136:137], v[36:37], v[28:29]
	v_addc_co_u32_e32 v121, vcc, 0, v129, vcc
	global_store_dwordx4 v[128:129], v[20:23], off nt
	global_store_dwordx4 v[118:119], v[24:27], off offset:-4096 nt
	global_store_dwordx4 v[118:119], v[32:35], off nt
	global_store_dwordx4 v[120:121], v[28:31], off nt
	s_nop 1
	v_mov_b32_e32 v110, v160
	v_mov_b32_e32 v111, v161
	v_mov_b32_e32 v112, v162
	v_mov_b32_e32 v113, v163
	v_mov_b32_e32 v36, v39
	v_mov_b32_e32 v37, v41
	v_pk_mul_f32 v[36:37], v[56:57], v[36:37] op_sel_hi:[0,1]
	v_mov_b32_e32 v39, v40
	v_pk_mul_f32 v[38:39], v[56:57], v[38:39] op_sel_hi:[0,1]
	v_mov_b32_e32 v40, v115
	v_mov_b32_e32 v41, v117
	v_mov_b32_e32 v115, v116
	v_add_co_u32_e32 v122, vcc, s22, v128
	v_mov_b32_e32 v62, v87
	s_nop 0
	v_addc_co_u32_e32 v123, vcc, 0, v129, vcc
	v_pk_mul_f32 v[86:87], v[56:57], v[88:89] op_sel_hi:[0,1]
	v_pk_mul_f32 v[62:63], v[56:57], v[62:63] op_sel_hi:[0,1]
	v_mov_b32_e32 v56, v59
	v_pk_mul_f32 v[88:89], v[58:59], v[60:61] op_sel_hi:[0,1]
	s_andn2_b64 vcc, exec, s[30:31]
	v_pk_fma_f32 v[14:15], v[36:37], v[112:113], v[14:15]
	v_mov_b32_e32 v36, v43
	v_mov_b32_e32 v37, v95
	v_pk_mul_f32 v[36:37], v[58:59], v[36:37] op_sel_hi:[0,1]
	v_mov_b32_e32 v43, v94
	v_pk_fma_f32 v[12:13], v[38:39], v[110:111], v[12:13]
	v_pk_mul_f32 v[38:39], v[58:59], v[42:43] op_sel_hi:[0,1]
	v_pk_fma_f32 v[18:19], v[36:37], v[112:113], v[18:19]
	v_mov_b32_e32 v36, v105
	v_mov_b32_e32 v37, v107
	v_mov_b32_e32 v105, v106
	v_pk_fma_f32 v[16:17], v[38:39], v[110:111], v[16:17]
	v_pk_mul_f32 v[38:39], v[76:77], v[36:37] op_sel_hi:[0,1]
	v_pk_mul_f32 v[36:37], v[76:77], v[104:105] op_sel_hi:[0,1]
	v_pk_mul_f32 v[42:43], v[82:83], v[40:41] op_sel_hi:[0,1]
	v_pk_mul_f32 v[40:41], v[82:83], v[114:115] op_sel_hi:[0,1]
	v_pk_fma_f32 v[36:37], v[110:111], v[36:37], v[140:141]
	v_pk_fma_f32 v[38:39], v[112:113], v[38:39], v[142:143]
	v_pk_fma_f32 v[40:41], v[110:111], v[40:41], v[100:101]
	v_pk_fma_f32 v[42:43], v[112:113], v[42:43], v[102:103]
	global_store_dwordx4 v[128:129], v[12:15], off offset:1024 nt
	global_store_dwordx4 v[122:123], v[16:19], off offset:1024 nt
	global_store_dwordx4 v[118:119], v[36:39], off offset:1024 nt
	global_store_dwordx4 v[120:121], v[40:43], off offset:1024 nt
	s_nop 1
	v_mov_b32_e32 v100, v164
	v_mov_b32_e32 v101, v165
	v_mov_b32_e32 v102, v166
	v_mov_b32_e32 v103, v167
	v_pk_fma_f32 v[4:5], v[48:49], v[100:101], v[4:5]
	v_pk_fma_f32 v[6:7], v[50:51], v[102:103], v[6:7]
	v_pk_mul_f32 v[48:49], v[58:59], v[92:93] op_sel_hi:[0,1]
	v_pk_mul_f32 v[50:51], v[58:59], v[90:91] op_sel_hi:[0,1]
	v_pk_fma_f32 v[8:9], v[50:51], v[100:101], v[8:9]
	v_pk_fma_f32 v[10:11], v[48:49], v[102:103], v[10:11]
	v_pk_mul_f32 v[48:49], v[76:77], v[98:99] op_sel_hi:[0,1]
	v_pk_mul_f32 v[50:51], v[76:77], v[96:97] op_sel_hi:[0,1]
	v_pk_fma_f32 v[44:45], v[50:51], v[100:101], v[44:45]
	v_pk_fma_f32 v[46:47], v[48:49], v[102:103], v[46:47]
	v_pk_mul_f32 v[50:51], v[82:83], v[126:127] op_sel_hi:[0,1]
	v_pk_mul_f32 v[48:49], v[82:83], v[108:109] op_sel_hi:[0,1]
	v_pk_fma_f32 v[48:49], v[100:101], v[48:49], v[144:145]
	v_pk_fma_f32 v[50:51], v[102:103], v[50:51], v[146:147]
	global_store_dwordx4 v[128:129], v[4:7], off offset:2048 nt
	global_store_dwordx4 v[122:123], v[8:11], off offset:2048 nt
	global_store_dwordx4 v[118:119], v[44:47], off offset:2048 nt
	global_store_dwordx4 v[120:121], v[48:51], off offset:2048 nt
	s_nop 1
	v_mov_b32_e32 v90, v168
	v_mov_b32_e32 v91, v169
	v_mov_b32_e32 v92, v170
	v_mov_b32_e32 v93, v171
	v_pk_fma_f32 v[60:61], v[62:63], v[90:91], v[0:1]
	v_pk_mul_f32 v[0:1], v[58:59], v[56:57] op_sel_hi:[0,1]
	v_pk_fma_f32 v[62:63], v[86:87], v[92:93], v[2:3]
	v_pk_fma_f32 v[56:57], v[0:1], v[90:91], v[52:53]
	v_pk_mul_f32 v[0:1], v[76:77], v[78:79] op_sel_hi:[0,1]
	v_pk_mul_f32 v[2:3], v[76:77], v[74:75] op_sel_hi:[0,1]
	v_pk_fma_f32 v[58:59], v[88:89], v[92:93], v[54:55]
	v_pk_fma_f32 v[52:53], v[2:3], v[90:91], v[64:65]
	v_pk_fma_f32 v[54:55], v[0:1], v[92:93], v[66:67]
	v_pk_mul_f32 v[2:3], v[82:83], v[84:85] op_sel_hi:[0,1]
	v_pk_mul_f32 v[0:1], v[82:83], v[80:81] op_sel_hi:[0,1]
	v_pk_fma_f32 v[0:1], v[0:1], v[90:91], v[148:149]
	v_pk_fma_f32 v[2:3], v[2:3], v[92:93], v[150:151]
	global_store_dwordx4 v[128:129], v[60:63], off offset:3072 nt
	global_store_dwordx4 v[122:123], v[56:59], off offset:3072 nt
	global_store_dwordx4 v[118:119], v[52:55], off offset:3072 nt
	global_store_dwordx4 v[120:121], v[0:3], off offset:3072 nt
	s_cbranch_vccnz .LBB0_208
; __device__ __forceinline__ void ew_post(const bf16* Y, const float* xin, float* xout, const float* gpost, const float* gnext, bf16* H, int gw, int ngw, int lane) {
;     ...
;                 s2[q] += (xv[q][j].x * xv[q][j].x + xv[q][j].y * xv[q][j].y) + (xv[q][j].z * xv[q][j].z + xv[q][j].w * xv[q][j].w); } }
;         if (gnext) {
;             float r2[EW_NR];
; #pragma unroll
;             for (int q = 0; q < EW_NR; ++q) r2[q] = rsqrtf(wave_sum(s2[q]) * (1.f / DM) + RMS_EPS);
; #pragma unroll
;             for (int j = 0; j < 4; ++j) { const f32x4 g = *((const f32x4*)gnext + lane + 64 * j);
	v_pk_mul_f32 v[64:65], v[30:31], v[30:31]
	v_pk_mul_f32 v[66:67], v[28:29], v[28:29]
	v_mul_f32_e32 v78, v1, v1
	v_pk_mov_b32 v[74:75], v[66:67], v[64:65] op_sel:[1,0]
	v_mov_b32_e32 v67, v65
	v_pk_add_f32 v[64:65], v[74:75], v[66:67]
	v_pk_mul_f32 v[66:67], v[42:43], v[42:43]
	v_pk_mul_f32 v[74:75], v[40:41], v[40:41]
	v_mul_f32_e32 v79, v2, v2
	v_pk_mov_b32 v[76:77], v[74:75], v[66:67] op_sel:[1,0]
	v_mov_b32_e32 v75, v67
	v_pk_add_f32 v[66:67], v[76:77], v[74:75]
	v_mul_f32_e32 v74, v49, v49
	v_mul_f32_e32 v76, v0, v0
	v_pk_fma_f32 v[74:75], v[48:49], v[48:49], v[74:75] op_sel_hi:[1,1,0]
	v_mul_f32_e32 v80, v3, v3
	v_mov_b32_e32 v75, v76
	v_mul_f32_e32 v76, v51, v51
	v_pk_fma_f32 v[76:77], v[50:51], v[50:51], v[76:77] op_sel_hi:[1,1,0]
	v_pk_add_f32 v[64:65], v[64:65], v[64:65] op_sel:[0,1] op_sel_hi:[1,0]
	v_pk_add_f32 v[66:67], v[66:67], v[66:67] op_sel:[0,1] op_sel_hi:[1,0]
	v_mov_b32_e32 v77, v78
	v_mov_b32_e32 v65, v79
	v_mov_b32_e32 v67, v80
	v_pk_add_f32 v[74:75], v[74:75], v[76:77]
	v_pk_add_f32 v[64:65], v[64:65], v[66:67]
	v_pk_mul_f32 v[66:67], v[34:35], v[34:35]
	v_pk_add_f32 v[64:65], v[74:75], v[64:65]
	v_pk_mul_f32 v[74:75], v[32:33], v[32:33]
	v_mul_f32_e32 v86, v53, v53
	v_pk_mov_b32 v[76:77], v[74:75], v[66:67] op_sel:[1,0]
	v_mov_b32_e32 v75, v67
	v_pk_add_f32 v[66:67], v[76:77], v[74:75]
	v_pk_mul_f32 v[74:75], v[38:39], v[38:39]
	v_pk_mul_f32 v[76:77], v[36:37], v[36:37]
	v_pk_add_f32 v[66:67], v[66:67], v[66:67] op_sel:[0,1] op_sel_hi:[1,0]
	v_pk_mov_b32 v[78:79], v[76:77], v[74:75] op_sel:[1,0]
	v_mov_b32_e32 v77, v75
	v_pk_add_f32 v[74:75], v[78:79], v[76:77]
	v_mul_f32_e32 v76, v52, v52
	v_mov_b32_e32 v67, v76
	v_pk_mul_f32 v[76:77], v[26:27], v[26:27]
	v_pk_mul_f32 v[78:79], v[24:25], v[24:25]
	v_mul_f32_e32 v87, v54, v54
	v_pk_mov_b32 v[80:81], v[78:79], v[76:77] op_sel:[1,0]
	v_mov_b32_e32 v79, v77
	v_pk_add_f32 v[76:77], v[80:81], v[78:79]
	v_pk_mul_f32 v[78:79], v[18:19], v[18:19]
	v_pk_mul_f32 v[80:81], v[16:17], v[16:17]
	v_pk_add_f32 v[76:77], v[76:77], v[76:77] op_sel:[0,1] op_sel_hi:[1,0]
	v_pk_mov_b32 v[82:83], v[80:81], v[78:79] op_sel:[1,0]
	v_mov_b32_e32 v81, v79
	v_pk_add_f32 v[78:79], v[82:83], v[80:81]
	v_mul_f32_e32 v80, v56, v56
	v_mul_f32_e32 v81, v57, v57
	v_pk_add_f32 v[78:79], v[78:79], v[78:79] op_sel:[0,1] op_sel_hi:[1,0]
	v_mov_b32_e32 v77, v80
	v_mov_b32_e32 v79, v81
	v_pk_add_f32 v[76:77], v[76:77], v[78:79]
	v_mul_f32_e32 v78, v9, v9
	v_mul_f32_e32 v80, v11, v11
	v_mul_f32_e32 v82, v58, v58
	v_mul_f32_e32 v83, v59, v59
	v_pk_fma_f32 v[78:79], v[8:9], v[8:9], v[78:79] op_sel_hi:[1,1,0]
	v_pk_fma_f32 v[80:81], v[10:11], v[10:11], v[80:81] op_sel_hi:[1,1,0]
	v_mov_b32_e32 v79, v82
	v_mov_b32_e32 v81, v83
	v_pk_add_f32 v[78:79], v[78:79], v[80:81]
	v_pk_mul_f32 v[80:81], v[20:21], v[20:21]
	v_pk_add_f32 v[76:77], v[76:77], v[78:79]
	v_pk_mul_f32 v[78:79], v[22:23], v[22:23]
	v_mul_f32_e32 v88, v55, v55
	v_pk_mov_b32 v[82:83], v[80:81], v[78:79] op_sel:[1,0]
	v_mov_b32_e32 v81, v79
	v_pk_add_f32 v[78:79], v[82:83], v[80:81]
	v_pk_mul_f32 v[80:81], v[14:15], v[14:15]
	v_pk_mul_f32 v[82:83], v[12:13], v[12:13]
	v_pk_add_f32 v[78:79], v[78:79], v[78:79] op_sel:[0,1] op_sel_hi:[1,0]
	v_pk_mov_b32 v[84:85], v[82:83], v[80:81] op_sel:[1,0]
	v_mov_b32_e32 v83, v81
	v_pk_add_f32 v[80:81], v[84:85], v[82:83]
	v_mul_f32_e32 v82, v60, v60
	v_mul_f32_e32 v83, v61, v61
	v_pk_add_f32 v[80:81], v[80:81], v[80:81] op_sel:[0,1] op_sel_hi:[1,0]
	v_mov_b32_e32 v79, v82
	v_mov_b32_e32 v81, v83
	v_pk_add_f32 v[78:79], v[78:79], v[80:81]
	v_mul_f32_e32 v80, v5, v5
	v_mul_f32_e32 v82, v7, v7
	v_mul_f32_e32 v84, v62, v62
	v_mul_f32_e32 v85, v63, v63
	v_pk_fma_f32 v[80:81], v[4:5], v[4:5], v[80:81] op_sel_hi:[1,1,0]
	v_pk_fma_f32 v[82:83], v[6:7], v[6:7], v[82:83] op_sel_hi:[1,1,0]
	v_mov_b32_e32 v81, v84
	v_mov_b32_e32 v83, v85
	v_pk_add_f32 v[80:81], v[80:81], v[82:83]
	v_pk_add_f32 v[82:83], v[74:75], v[74:75] op_sel:[0,1] op_sel_hi:[1,0]
	v_pk_add_f32 v[78:79], v[78:79], v[80:81]
	v_mov_b32_e32 v80, v76
	v_mov_b32_e32 v81, v78
	v_mov_b32_e32 v78, v77
	s_nop 1
	v_mov_b32_e32 v74, v232
	v_mov_b32_e32 v75, v233
	v_mov_b32_e32 v76, v234
	v_mov_b32_e32 v77, v235
	v_pk_add_f32 v[78:79], v[80:81], v[78:79]
	v_mov_b32_e32 v83, v86
	ds_bpermute_b32 v81, v130, v79
	ds_bpermute_b32 v80, v130, v78
	v_pk_add_f32 v[66:67], v[66:67], v[82:83]
	v_mul_f32_e32 v82, v45, v45
	v_mul_f32_e32 v84, v47, v47
	v_pk_fma_f32 v[82:83], v[44:45], v[44:45], v[82:83] op_sel_hi:[1,1,0]
	v_pk_fma_f32 v[84:85], v[46:47], v[46:47], v[84:85] op_sel_hi:[1,1,0]
	v_mov_b32_e32 v83, v87
	v_mov_b32_e32 v85, v88
	v_pk_add_f32 v[82:83], v[82:83], v[84:85]
	s_waitcnt lgkmcnt(0)
	v_pk_add_f32 v[78:79], v[78:79], v[80:81]
	v_pk_add_f32 v[66:67], v[66:67], v[82:83]
	v_mov_b32_e32 v82, v64
	v_mov_b32_e32 v83, v66
	v_mov_b32_e32 v66, v65
	ds_bpermute_b32 v81, v131, v79
	ds_bpermute_b32 v80, v131, v78
	v_pk_add_f32 v[64:65], v[82:83], v[66:67]
	ds_bpermute_b32 v67, v130, v65
	ds_bpermute_b32 v66, v130, v64
	s_waitcnt lgkmcnt(2)
	v_pk_add_f32 v[78:79], v[78:79], v[80:81]
	ds_bpermute_b32 v81, v132, v79
	ds_bpermute_b32 v80, v132, v78
	s_waitcnt lgkmcnt(2)
	v_pk_add_f32 v[64:65], v[64:65], v[66:67]
	ds_bpermute_b32 v67, v131, v65
	ds_bpermute_b32 v66, v131, v64
	s_waitcnt lgkmcnt(2)
	v_pk_add_f32 v[78:79], v[78:79], v[80:81]
	ds_bpermute_b32 v81, v133, v79
	ds_bpermute_b32 v80, v133, v78
	s_waitcnt lgkmcnt(2)
	v_pk_add_f32 v[64:65], v[64:65], v[66:67]
	ds_bpermute_b32 v67, v132, v65
	ds_bpermute_b32 v66, v132, v64
	s_waitcnt lgkmcnt(2)
	v_pk_add_f32 v[78:79], v[78:79], v[80:81]
	ds_bpermute_b32 v81, v134, v79
	ds_bpermute_b32 v80, v134, v78
	s_waitcnt lgkmcnt(2)
; __device__ __forceinline__ void ew_post(const bf16* Y, const float* xin, float* xout, const float* gpost, const float* gnext, bf16* H, int gw, int ngw, int lane) {
;     ...
;             for (int q = 0; q < EW_NR; ++q) r2[q] = rsqrtf(wave_sum(s2[q]) * (1.f / DM) + RMS_EPS);
; #pragma unroll
;             for (int j = 0; j < 4; ++j) { const f32x4 g = *((const f32x4*)gnext + lane + 64 * j);
	v_pk_add_f32 v[64:65], v[64:65], v[66:67]
	ds_bpermute_b32 v67, v133, v65
	ds_bpermute_b32 v66, v133, v64
	s_waitcnt lgkmcnt(2)
	v_pk_add_f32 v[78:79], v[78:79], v[80:81]
	ds_bpermute_b32 v81, v135, v79
	ds_bpermute_b32 v80, v135, v78
	s_waitcnt lgkmcnt(2)
	v_pk_add_f32 v[64:65], v[64:65], v[66:67]
	ds_bpermute_b32 v67, v134, v65
	ds_bpermute_b32 v66, v134, v64
	s_waitcnt lgkmcnt(2)
	v_pk_add_f32 v[78:79], v[78:79], v[80:81]
	v_mov_b64_e32 v[80:81], s[26:27]
	v_pk_fma_f32 v[78:79], v[78:79], s[44:45], v[80:81] op_sel_hi:[1,0,0]
	s_waitcnt lgkmcnt(0)
	v_pk_add_f32 v[64:65], v[64:65], v[66:67]
	v_mul_f32_e32 v82, 0x4b800000, v79
	v_cmp_gt_f32_e32 vcc, s3, v79
	ds_bpermute_b32 v67, v135, v65
	ds_bpermute_b32 v66, v135, v64
	v_cndmask_b32_e32 v79, v79, v82, vcc
	v_rsq_f32_e32 v79, v79
	v_mul_f32_e32 v82, 0x4b800000, v78
	v_cmp_gt_f32_e64 s[4:5], s3, v78
	s_waitcnt lgkmcnt(0)
; __device__ __forceinline__ unsigned pk2(float lo, float hi) { f32v2 v = {lo, hi}; bf16v2 r = __builtin_convertvector(v, bf16v2); return __builtin_bit_cast(unsigned, r); }
; __device__ __forceinline__ void ew_post(const bf16* Y, const float* xin, float* xout, const float* gpost, const float* gnext, bf16* H, int gw, int ngw, int lane) {
;     ...
; #pragma unroll
;             for (int j = 0; j < 4; ++j) { const f32x4 g = *((const f32x4*)gnext + lane + 64 * j);
; #pragma unroll
;                 for (int q = 0; q < EW_NR; ++q) { v2u w; w.x = pk2(xv[q][j].x * r2[q] * g.x, xv[q][j].y * r2[q] * g.y); w.y = pk2(xv[q][j].z * r2[q] * g.z, xv[q][j].w * r2[q] * g.w);
;                     *((v2u*)(H + (size_t)(m0 + q) * DM) + lane + 64 * j) = w; } }
	v_pk_add_f32 v[64:65], v[64:65], v[66:67]
	v_cndmask_b32_e64 v78, v78, v82, s[4:5]
	v_rsq_f32_e32 v82, v78
	v_mul_f32_e32 v78, 0x45800000, v79
	v_pk_fma_f32 v[64:65], v[64:65], s[44:45], v[80:81] op_sel_hi:[1,0,0]
	v_cndmask_b32_e32 v78, v79, v78, vcc
	v_mul_f32_e32 v66, 0x4b800000, v65
	v_cmp_gt_f32_e32 vcc, s3, v65
	v_mul_f32_e32 v79, 0x45800000, v82
	v_cmp_gt_f32_e64 s[6:7], s3, v64
	v_cndmask_b32_e32 v65, v65, v66, vcc
	v_rsq_f32_e32 v65, v65
	v_mul_f32_e32 v66, 0x4b800000, v64
	v_pk_mul_f32 v[20:21], v[20:21], v[78:79] op_sel_hi:[1,0]
	v_pk_mul_f32 v[22:23], v[22:23], v[78:79] op_sel_hi:[1,0]
	v_mul_f32_e32 v67, 0x45800000, v65
	v_cndmask_b32_e64 v64, v64, v66, s[6:7]
	v_cndmask_b32_e64 v66, v82, v79, s[4:5]
	v_cndmask_b32_e32 v80, v65, v67, vcc
	v_pk_mul_f32 v[20:21], v[20:21], v[74:75]
	v_pk_mul_f32 v[22:23], v[22:23], v[76:77]
	v_add_co_u32_e32 v82, vcc, s20, v72
	v_cvt_pk_bf16_f32 v20, v20, v21
	v_cvt_pk_bf16_f32 v21, v22, v23
	v_addc_co_u32_e32 v83, vcc, -1, v73, vcc
	v_rsq_f32_e32 v64, v64
	global_store_dwordx2 v[82:83], v[20:21], off offset:-3584
	v_pk_mul_f32 v[20:21], v[24:25], v[66:67] op_sel_hi:[1,0]
	v_pk_mul_f32 v[22:23], v[26:27], v[66:67] op_sel_hi:[1,0]
	v_pk_mul_f32 v[20:21], v[20:21], v[74:75]
	v_pk_mul_f32 v[22:23], v[22:23], v[76:77]
	v_cvt_pk_bf16_f32 v20, v20, v21
	v_cvt_pk_bf16_f32 v21, v22, v23
	global_store_dwordx2 v[82:83], v[20:21], off offset:-1536
	v_pk_mul_f32 v[20:21], v[32:33], v[80:81] op_sel_hi:[1,0]
	v_pk_mul_f32 v[22:23], v[34:35], v[80:81] op_sel_hi:[1,0]
	v_mul_f32_e32 v65, 0x45800000, v64
	v_pk_mul_f32 v[20:21], v[74:75], v[20:21]
	v_pk_mul_f32 v[22:23], v[76:77], v[22:23]
	v_add_co_u32_e32 v24, vcc, s21, v72
	v_cndmask_b32_e64 v64, v64, v65, s[6:7]
	v_cvt_pk_bf16_f32 v20, v20, v21
	v_cvt_pk_bf16_f32 v21, v22, v23
	v_addc_co_u32_e32 v25, vcc, -1, v73, vcc
	global_store_dwordx2 v[24:25], v[20:21], off offset:-3584
	v_pk_mul_f32 v[20:21], v[28:29], v[64:65] op_sel_hi:[1,0]
	v_pk_mul_f32 v[22:23], v[30:31], v[64:65] op_sel_hi:[1,0]
	v_pk_mul_f32 v[20:21], v[74:75], v[20:21]
	v_pk_mul_f32 v[22:23], v[76:77], v[22:23]
	v_cvt_pk_bf16_f32 v20, v20, v21
	v_cvt_pk_bf16_f32 v21, v22, v23
	global_store_dwordx2 v[24:25], v[20:21], off offset:-1536
	s_nop 1
	v_mov_b32_e32 v20, v236
	v_mov_b32_e32 v21, v237
	v_mov_b32_e32 v22, v238
	v_mov_b32_e32 v23, v239
	v_pk_mul_f32 v[12:13], v[12:13], v[78:79] op_sel_hi:[1,0]
	v_pk_mul_f32 v[14:15], v[14:15], v[78:79] op_sel_hi:[1,0]
	v_pk_mul_f32 v[4:5], v[4:5], v[78:79] op_sel_hi:[1,0]
	v_pk_mul_f32 v[6:7], v[6:7], v[78:79] op_sel_hi:[1,0]
	v_pk_mul_f32 v[0:1], v[0:1], v[64:65] op_sel_hi:[1,0]
	v_pk_mul_f32 v[2:3], v[2:3], v[64:65] op_sel_hi:[1,0]
	v_pk_mul_f32 v[12:13], v[12:13], v[20:21]
	v_pk_mul_f32 v[14:15], v[14:15], v[22:23]
	v_cvt_pk_bf16_f32 v12, v12, v13
	v_cvt_pk_bf16_f32 v13, v14, v15
	global_store_dwordx2 v[82:83], v[12:13], off offset:-3072
	v_pk_mul_f32 v[12:13], v[16:17], v[66:67] op_sel_hi:[1,0]
	v_pk_mul_f32 v[14:15], v[18:19], v[66:67] op_sel_hi:[1,0]
	v_pk_mul_f32 v[12:13], v[12:13], v[20:21]
	v_pk_mul_f32 v[14:15], v[14:15], v[22:23]
	v_cvt_pk_bf16_f32 v12, v12, v13
	v_cvt_pk_bf16_f32 v13, v14, v15
	global_store_dwordx2 v[82:83], v[12:13], off offset:-1024
	v_pk_mul_f32 v[12:13], v[36:37], v[80:81] op_sel_hi:[1,0]
	v_pk_mul_f32 v[14:15], v[38:39], v[80:81] op_sel_hi:[1,0]
	v_pk_mul_f32 v[12:13], v[12:13], v[20:21]
	v_pk_mul_f32 v[14:15], v[14:15], v[22:23]
	v_cvt_pk_bf16_f32 v12, v12, v13
	v_cvt_pk_bf16_f32 v13, v14, v15
	global_store_dwordx2 v[24:25], v[12:13], off offset:-3072
	v_pk_mul_f32 v[12:13], v[40:41], v[64:65] op_sel_hi:[1,0]
	v_pk_mul_f32 v[14:15], v[42:43], v[64:65] op_sel_hi:[1,0]
	v_pk_mul_f32 v[12:13], v[20:21], v[12:13]
	v_pk_mul_f32 v[14:15], v[22:23], v[14:15]
	v_cvt_pk_bf16_f32 v12, v12, v13
	v_cvt_pk_bf16_f32 v13, v14, v15
	global_store_dwordx2 v[24:25], v[12:13], off offset:-1024
	s_nop 1
	v_mov_b32_e32 v12, v240
	v_mov_b32_e32 v13, v241
	v_mov_b32_e32 v14, v242
	v_mov_b32_e32 v15, v243
	v_pk_mul_f32 v[16:17], v[52:53], v[80:81] op_sel_hi:[1,0]
	v_pk_mul_f32 v[18:19], v[54:55], v[80:81] op_sel_hi:[1,0]
	v_pk_mul_f32 v[4:5], v[4:5], v[12:13]
	v_pk_mul_f32 v[6:7], v[6:7], v[14:15]
	v_cvt_pk_bf16_f32 v4, v4, v5
	v_cvt_pk_bf16_f32 v5, v6, v7
	global_store_dwordx2 v[82:83], v[4:5], off offset:-2560
	v_pk_mul_f32 v[4:5], v[8:9], v[66:67] op_sel_hi:[1,0]
	v_pk_mul_f32 v[6:7], v[10:11], v[66:67] op_sel_hi:[1,0]
	v_pk_mul_f32 v[4:5], v[4:5], v[12:13]
	v_pk_mul_f32 v[6:7], v[6:7], v[14:15]
	v_cvt_pk_bf16_f32 v4, v4, v5
	v_cvt_pk_bf16_f32 v5, v6, v7
	global_store_dwordx2 v[82:83], v[4:5], off offset:-512
	v_pk_mul_f32 v[4:5], v[44:45], v[80:81] op_sel_hi:[1,0]
	v_pk_mul_f32 v[6:7], v[46:47], v[80:81] op_sel_hi:[1,0]
	v_pk_mul_f32 v[4:5], v[4:5], v[12:13]
	v_pk_mul_f32 v[6:7], v[6:7], v[14:15]
	v_cvt_pk_bf16_f32 v4, v4, v5
	v_cvt_pk_bf16_f32 v5, v6, v7
	global_store_dwordx2 v[24:25], v[4:5], off offset:-2560
	v_pk_mul_f32 v[4:5], v[48:49], v[64:65] op_sel_hi:[1,0]
	v_pk_mul_f32 v[6:7], v[50:51], v[64:65] op_sel_hi:[1,0]
	v_pk_mul_f32 v[4:5], v[4:5], v[12:13]
	v_pk_mul_f32 v[6:7], v[6:7], v[14:15]
	v_cvt_pk_bf16_f32 v4, v4, v5
	v_cvt_pk_bf16_f32 v5, v6, v7
	global_store_dwordx2 v[24:25], v[4:5], off offset:-512
	s_nop 1
	v_mov_b32_e32 v4, v244
	v_mov_b32_e32 v5, v245
	v_mov_b32_e32 v6, v246
	v_mov_b32_e32 v7, v247
	v_pk_mul_f32 v[8:9], v[60:61], v[78:79] op_sel_hi:[1,0]
	v_pk_mul_f32 v[10:11], v[62:63], v[78:79] op_sel_hi:[1,0]
	v_pk_mul_f32 v[12:13], v[56:57], v[66:67] op_sel_hi:[1,0]
	v_pk_mul_f32 v[14:15], v[58:59], v[66:67] op_sel_hi:[1,0]
	v_pk_mul_f32 v[8:9], v[8:9], v[4:5]
	v_pk_mul_f32 v[10:11], v[10:11], v[6:7]
	v_pk_mul_f32 v[12:13], v[12:13], v[4:5]
	v_pk_mul_f32 v[14:15], v[14:15], v[6:7]
	v_pk_mul_f32 v[16:17], v[16:17], v[4:5]
	v_pk_mul_f32 v[18:19], v[18:19], v[6:7]
	v_pk_mul_f32 v[0:1], v[0:1], v[4:5]
	v_pk_mul_f32 v[2:3], v[2:3], v[6:7]
	v_cvt_pk_bf16_f32 v4, v8, v9
	v_cvt_pk_bf16_f32 v5, v10, v11
	v_cvt_pk_bf16_f32 v6, v12, v13
	v_cvt_pk_bf16_f32 v7, v14, v15
	v_cvt_pk_bf16_f32 v8, v16, v17
	v_cvt_pk_bf16_f32 v9, v18, v19
	v_cvt_pk_bf16_f32 v0, v0, v1
	v_cvt_pk_bf16_f32 v1, v2, v3
	global_store_dwordx2 v[82:83], v[4:5], off offset:-2048
	global_store_dwordx2 v[24:25], v[6:7], off offset:-4096
	global_store_dwordx2 v[24:25], v[8:9], off offset:-2048
	global_store_dwordx2 v[24:25], v[0:1], off
	s_branch .LBB0_208
